# v27 + 25 GEMM staging loads use SGPR-base + 32-bit VGPR-offset addressing (64-bit VALU address adds dropped where the pair was single-use)
# baseline (speedup 1.0000x reference)
; #define PG8_STAGE(bufoff, gbase, voff) do { _Pragma("unroll") for (int _i = 0; _i < 2; ++_i) \
;         __builtin_amdgcn_global_load_lds((const unsigned*)((const char*)(gbase) + (voff)[_i]), (PG8_LAS unsigned*)(lds + (bufoff) + ldsw + _i * 8192), 16, 0, 0); } while (0)
; #define PG8_LDA(dst, b, h) do { _Pragma("unroll") for (int m = 0; m < 4; ++m) _Pragma("unroll") for (int k = 0; k < 2; ++k) dst[m][k] = *(const PG8_LAS bf16x8*)(lds + PG8_SA(b, h) + aoff + m * 2048 + k * 1024); } while (0)
; #define PG8_LDB(dst, b, h) do { _Pragma("unroll") for (int n = 0; n < 2; ++n) _Pragma("unroll") for (int k = 0; k < 2; ++k) dst[n][k] = *(const PG8_LAS bf16x8*)(lds + PG8_SB(b, h) + boff + n * 2048 + k * 1024); } while (0)
; #define PG8_MMA(ai, bj, At, Bt) do { __builtin_amdgcn_s_setprio(1); _Pragma("unroll") for (int m = 0; m < 4; ++m) _Pragma("unroll") for (int n = 0; n < 2; ++n) _Pragma("unroll") for (int k = 0; k < 2; ++k) \
;         acc[ai][bj][m][n] = __builtin_amdgcn_mfma_f32_16x16x32_bf16(Bt[n][k], At[m][k], acc[ai][bj][m][n], 0, 0, 0); __builtin_amdgcn_s_setprio(0); } while (0)
; #define PG8_WAIT_V(n) asm volatile("s_waitcnt vmcnt(" #n ")" ::: "memory")
; #define PG8_BAR __builtin_amdgcn_s_barrier()
; template <class Epi, class Sched, bool ALIGN_EPI = false, bool SP2 = false>
; __device__ __forceinline__ void gemm_phase(PG8_LAS unsigned char* lds, const Gemm g, const Sched& S, const Epi& E) {
;     ...
;         for (int t = 0; t < nt; t += 2) {
;             const bool last = (t == nt - 2);
;             const char* a1 = cA + (size_t)(t + 1) * kstep;
;             const char* a2 = last ? nA : cA + (size_t)(t + 2) * kstep; const char* b2 = last ? nB : cB + (size_t)(t + 2) * kstep;
;             const char* a3 = a2 + kstep; const char* b3 = b2 + kstep;
;             if (last && has_next) S.a_ready(nxt);
;             if constexpr (SP2) {
;             PG8_LDB(B0, 0, 0); PG8_LDB(B1, 0, 1); PG8_SCHED; PG8_LDA(At, 0, 0); PG8_STAGE(PG8_SA(1, 1), a1 + hstep, voffA);
;             PG8_WAIT_V(8); PG8_WAIT_L(0); PG8_BAR; PG8_MMA(0, 0, At, B0); PG8_MMA(0, 1, At, B1); PG8_BAR; PG8_SCHED;
;             PG8_LDA(At, 0, 1); PG8_STAGE(PG8_SB(0, 0), b2, voffB); PG8_STAGE(PG8_SB(0, 1), b2 + hstep, voffB); PG8_STAGE(PG8_SA(0, 0), a2, voffA);
;             PG8_WAIT_V(8); PG8_WAIT_L(0); PG8_BAR; PG8_MMA(1, 0, At, B0); PG8_MMA(1, 1, At, B1); PG8_BAR; PG8_SCHED;
.LBB0_146:
	s_add_u32 s44, s24, 0xfff80080
	s_addc_u32 s45, s25, -1
	s_add_i32 s55, 0, 0x10000
	s_cmp_eq_u32 s54, 28
	s_cselect_b32 s47, s21, s45
	s_cselect_b32 s46, s48, s44
	v_add_u32_e32 v167, s55, v147
	s_cselect_b32 s45, s19, s51
	s_cselect_b32 s44, s49, s50
	s_add_i32 s62, 0, 0x14000
	ds_read_b128 v[142:145], v167
	ds_read_b128 v[168:171], v167 offset:1024
	ds_read_b128 v[172:175], v167 offset:2048
	ds_read_b128 v[176:179], v167 offset:3072
	v_add_u32_e32 v167, s62, v147
	ds_read_b128 v[180:183], v167
	ds_read_b128 v[184:187], v167 offset:1024
	ds_read_b128 v[188:191], v167 offset:2048
	ds_read_b128 v[204:207], v167 offset:3072
	v_lshl_add_u64 v[192:193], s[24:25], 0, v[138:139]
	s_add_i32 m0, s1, 0xc000
	ds_read_b128 v[216:219], v166
	ds_read_b128 v[220:223], v166 offset:1024
	ds_read_b128 v[224:227], v166 offset:2048
	ds_read_b128 v[228:231], v166 offset:3072
	ds_read_b128 v[232:235], v166 offset:4096
	ds_read_b128 v[236:239], v166 offset:5120
	ds_read_b128 v[240:243], v166 offset:6144
	ds_read_b128 v[244:247], v166 offset:7168
	global_load_lds_dwordx4 v[192:193], off
	s_nop 0
	s_add_i32 m0, s1, 0xe000
	s_nop 0
	global_load_lds_dwordx4 v140, s[24:25]
	s_waitcnt vmcnt(8)
	s_waitcnt lgkmcnt(0)
	s_setprio 1
	s_barrier
	v_mfma_f32_16x16x32_bf16 v[126:129], v[142:145], v[216:219], v[126:129]
	v_mfma_f32_16x16x32_bf16 v[122:125], v[172:175], v[216:219], v[122:125]
	v_mfma_f32_16x16x32_bf16 v[114:117], v[142:145], v[224:227], v[114:117]
	v_mfma_f32_16x16x32_bf16 v[106:109], v[172:175], v[224:227], v[106:109]
	v_mfma_f32_16x16x32_bf16 v[98:101], v[142:145], v[232:235], v[98:101]
	v_mfma_f32_16x16x32_bf16 v[90:93], v[172:175], v[232:235], v[90:93]
	v_mfma_f32_16x16x32_bf16 v[82:85], v[142:145], v[240:243], v[82:85]
	v_mfma_f32_16x16x32_bf16 v[74:77], v[172:175], v[240:243], v[74:77]
	v_mfma_f32_16x16x32_bf16 v[126:129], v[168:171], v[220:223], v[126:129]
	v_mfma_f32_16x16x32_bf16 v[122:125], v[176:179], v[220:223], v[122:125]
	v_mfma_f32_16x16x32_bf16 v[114:117], v[168:171], v[228:231], v[114:117]
	v_mfma_f32_16x16x32_bf16 v[106:109], v[176:179], v[228:231], v[106:109]
	v_mfma_f32_16x16x32_bf16 v[98:101], v[168:171], v[236:239], v[98:101]
	v_mfma_f32_16x16x32_bf16 v[90:93], v[176:179], v[236:239], v[90:93]
	v_mfma_f32_16x16x32_bf16 v[82:85], v[168:171], v[244:247], v[82:85]
	v_mfma_f32_16x16x32_bf16 v[74:77], v[176:179], v[244:247], v[74:77]
	s_setprio 0
	s_setprio 1
	v_mfma_f32_16x16x32_bf16 v[118:121], v[180:183], v[216:219], v[118:121]
	v_mfma_f32_16x16x32_bf16 v[110:113], v[188:191], v[216:219], v[110:113]
	v_mfma_f32_16x16x32_bf16 v[102:105], v[180:183], v[224:227], v[102:105]
	v_mfma_f32_16x16x32_bf16 v[94:97], v[188:191], v[224:227], v[94:97]
	v_mfma_f32_16x16x32_bf16 v[86:89], v[180:183], v[232:235], v[86:89]
	v_mfma_f32_16x16x32_bf16 v[78:81], v[188:191], v[232:235], v[78:81]
	v_mfma_f32_16x16x32_bf16 v[70:73], v[180:183], v[240:243], v[70:73]
	v_mfma_f32_16x16x32_bf16 v[66:69], v[188:191], v[240:243], v[66:69]
	v_mfma_f32_16x16x32_bf16 v[118:121], v[184:187], v[220:223], v[118:121]
	v_mfma_f32_16x16x32_bf16 v[110:113], v[204:207], v[220:223], v[110:113]
	v_mfma_f32_16x16x32_bf16 v[102:105], v[184:187], v[228:231], v[102:105]
	v_mfma_f32_16x16x32_bf16 v[94:97], v[204:207], v[228:231], v[94:97]
	v_mfma_f32_16x16x32_bf16 v[86:89], v[184:187], v[236:239], v[86:89]
	v_mfma_f32_16x16x32_bf16 v[78:81], v[204:207], v[236:239], v[78:81]
	v_mfma_f32_16x16x32_bf16 v[70:73], v[184:187], v[244:247], v[70:73]
	v_mfma_f32_16x16x32_bf16 v[66:69], v[204:207], v[244:247], v[66:69]
	s_barrier
	s_setprio 0
	s_add_i32 s55, s55, s0
	v_lshl_add_u64 v[192:193], s[44:45], 0, v[0:1]
	s_mov_b32 m0, s55
	ds_read_b128 v[216:219], v166 offset:16384
	ds_read_b128 v[220:223], v166 offset:17408
	ds_read_b128 v[224:227], v166 offset:18432
	ds_read_b128 v[228:231], v166 offset:19456
	ds_read_b128 v[232:235], v166 offset:20480
	ds_read_b128 v[236:239], v166 offset:21504
	ds_read_b128 v[240:243], v166 offset:22528
	ds_read_b128 v[244:247], v166 offset:23552
	global_load_lds_dwordx4 v[192:193], off
	s_add_i32 m0, s55, 0x2000
	s_add_u32 s58, s44, 0x80000
	v_lshl_add_u64 v[248:249], s[44:45], 0, v[130:131]
	s_addc_u32 s59, s45, 0
	s_add_i32 s55, s62, s0
	global_load_lds_dwordx4 v[248:249], off
	s_nop 0
	s_mov_b32 m0, s55
	v_lshl_add_u64 v[200:201], s[46:47], 0, v[132:133]
	global_load_lds_dwordx4 v0, s[58:59]
	s_nop 0
	s_add_i32 m0, s55, 0x2000
	s_nop 0
	global_load_lds_dwordx4 v130, s[58:59]
	v_lshl_add_u64 v[250:251], s[46:47], 0, v[134:135]
	s_mov_b32 m0, s1
	s_nop 0
	global_load_lds_dwordx4 v[250:251], off
	s_mov_b32 m0, s2
	s_nop 0
	global_load_lds_dwordx4 v[200:201], off
	s_waitcnt vmcnt(8)
	s_waitcnt lgkmcnt(0)
	s_setprio 1
	s_barrier
; #define PG8_STAGE(bufoff, gbase, voff) do { _Pragma("unroll") for (int _i = 0; _i < 2; ++_i) \
;         __builtin_amdgcn_global_load_lds((const unsigned*)((const char*)(gbase) + (voff)[_i]), (PG8_LAS unsigned*)(lds + (bufoff) + ldsw + _i * 8192), 16, 0, 0); } while (0)
; #define PG8_LDA(dst, b, h) do { _Pragma("unroll") for (int m = 0; m < 4; ++m) _Pragma("unroll") for (int k = 0; k < 2; ++k) dst[m][k] = *(const PG8_LAS bf16x8*)(lds + PG8_SA(b, h) + aoff + m * 2048 + k * 1024); } while (0)
; #define PG8_LDB(dst, b, h) do { _Pragma("unroll") for (int n = 0; n < 2; ++n) _Pragma("unroll") for (int k = 0; k < 2; ++k) dst[n][k] = *(const PG8_LAS bf16x8*)(lds + PG8_SB(b, h) + boff + n * 2048 + k * 1024); } while (0)
; #define PG8_MMA(ai, bj, At, Bt) do { __builtin_amdgcn_s_setprio(1); _Pragma("unroll") for (int m = 0; m < 4; ++m) _Pragma("unroll") for (int n = 0; n < 2; ++n) _Pragma("unroll") for (int k = 0; k < 2; ++k) \
;         acc[ai][bj][m][n] = __builtin_amdgcn_mfma_f32_16x16x32_bf16(Bt[n][k], At[m][k], acc[ai][bj][m][n], 0, 0, 0); __builtin_amdgcn_s_setprio(0); } while (0)
; #define PG8_WAIT_V(n) asm volatile("s_waitcnt vmcnt(" #n ")" ::: "memory")
; #define PG8_WAIT_L(n) asm volatile("s_waitcnt lgkmcnt(" #n ")" ::: "memory")
; #define PG8_BAR __builtin_amdgcn_s_barrier()
; #define PG8_SCHED __builtin_amdgcn_sched_barrier(0)
; template <class Epi, class Sched, bool ALIGN_EPI = false, bool SP2 = false>
; __device__ __forceinline__ void gemm_phase(PG8_LAS unsigned char* lds, const Gemm g, const Sched& S, const Epi& E) {
;     ...
;             PG8_WAIT_V(8); PG8_WAIT_L(0); PG8_BAR; PG8_MMA(1, 0, At, B0); PG8_MMA(1, 1, At, B1); PG8_BAR; PG8_SCHED;
;             PG8_LDB(B0, 1, 0); PG8_LDB(B1, 1, 1); PG8_SCHED; PG8_LDA(At, 1, 0); PG8_STAGE(PG8_SA(0, 1), a2 + hstep, voffA);
;             PG8_WAIT_V(8); PG8_WAIT_L(0); PG8_BAR; PG8_MMA(0, 0, At, B0); PG8_MMA(0, 1, At, B1); PG8_BAR; PG8_SCHED;
;             PG8_LDA(At, 1, 1); PG8_STAGE(PG8_SB(1, 0), b3, voffB); PG8_STAGE(PG8_SB(1, 1), b3 + hstep, voffB); PG8_STAGE(PG8_SA(1, 0), a3, voffA);
	v_mfma_f32_16x16x32_bf16 v[62:65], v[142:145], v[216:219], v[62:65]
	v_mfma_f32_16x16x32_bf16 v[58:61], v[172:175], v[216:219], v[58:61]
	v_mfma_f32_16x16x32_bf16 v[50:53], v[142:145], v[224:227], v[50:53]
	v_mfma_f32_16x16x32_bf16 v[42:45], v[172:175], v[224:227], v[42:45]
	v_mfma_f32_16x16x32_bf16 v[34:37], v[142:145], v[232:235], v[34:37]
	v_mfma_f32_16x16x32_bf16 v[26:29], v[172:175], v[232:235], v[26:29]
	v_mfma_f32_16x16x32_bf16 v[18:21], v[142:145], v[240:243], v[18:21]
	v_mfma_f32_16x16x32_bf16 v[10:13], v[172:175], v[240:243], v[10:13]
	v_mfma_f32_16x16x32_bf16 v[62:65], v[168:171], v[220:223], v[62:65]
	v_mfma_f32_16x16x32_bf16 v[58:61], v[176:179], v[220:223], v[58:61]
	v_mfma_f32_16x16x32_bf16 v[50:53], v[168:171], v[228:231], v[50:53]
	v_mfma_f32_16x16x32_bf16 v[42:45], v[176:179], v[228:231], v[42:45]
	v_mfma_f32_16x16x32_bf16 v[34:37], v[168:171], v[236:239], v[34:37]
	v_mfma_f32_16x16x32_bf16 v[26:29], v[176:179], v[236:239], v[26:29]
	v_mfma_f32_16x16x32_bf16 v[18:21], v[168:171], v[244:247], v[18:21]
	v_mfma_f32_16x16x32_bf16 v[10:13], v[176:179], v[244:247], v[10:13]
	s_setprio 0
	s_setprio 1
	v_mfma_f32_16x16x32_bf16 v[54:57], v[180:183], v[216:219], v[54:57]
	v_mfma_f32_16x16x32_bf16 v[46:49], v[188:191], v[216:219], v[46:49]
	v_mfma_f32_16x16x32_bf16 v[38:41], v[180:183], v[224:227], v[38:41]
	v_mfma_f32_16x16x32_bf16 v[30:33], v[188:191], v[224:227], v[30:33]
	v_mfma_f32_16x16x32_bf16 v[22:25], v[180:183], v[232:235], v[22:25]
	v_mfma_f32_16x16x32_bf16 v[14:17], v[188:191], v[232:235], v[14:17]
	v_mfma_f32_16x16x32_bf16 v[6:9], v[180:183], v[240:243], v[6:9]
	v_mfma_f32_16x16x32_bf16 v[2:5], v[188:191], v[240:243], v[2:5]
	v_mfma_f32_16x16x32_bf16 v[54:57], v[184:187], v[220:223], v[54:57]
	v_mfma_f32_16x16x32_bf16 v[46:49], v[204:207], v[220:223], v[46:49]
	v_mfma_f32_16x16x32_bf16 v[38:41], v[184:187], v[228:231], v[38:41]
	v_mfma_f32_16x16x32_bf16 v[30:33], v[204:207], v[228:231], v[30:33]
	v_mfma_f32_16x16x32_bf16 v[22:25], v[184:187], v[236:239], v[22:25]
	v_mfma_f32_16x16x32_bf16 v[14:17], v[204:207], v[236:239], v[14:17]
	v_mfma_f32_16x16x32_bf16 v[6:9], v[184:187], v[244:247], v[6:9]
	v_mfma_f32_16x16x32_bf16 v[2:5], v[204:207], v[244:247], v[2:5]
	s_barrier
	s_setprio 0
	s_add_i32 s55, 0, 0x18000
	v_add_u32_e32 v167, s55, v147
	s_add_i32 s58, 0, 0x1c000
	ds_read_b128 v[142:145], v167
	ds_read_b128 v[168:171], v167 offset:1024
	ds_read_b128 v[172:175], v167 offset:2048
	ds_read_b128 v[176:179], v167 offset:3072
	v_add_u32_e32 v167, s58, v147
	ds_read_b128 v[180:183], v167
	ds_read_b128 v[184:187], v167 offset:1024
	ds_read_b128 v[188:191], v167 offset:2048
	ds_read_b128 v[204:207], v167 offset:3072
	s_add_u32 s46, s46, 0x80000
	s_addc_u32 s47, s47, 0
	s_mov_b32 m0, s3
	v_lshl_add_u64 v[202:203], s[46:47], 0, v[134:135]
	ds_read_b128 v[216:219], v166 offset:32768
	ds_read_b128 v[220:223], v166 offset:33792
	ds_read_b128 v[224:227], v166 offset:34816
	ds_read_b128 v[228:231], v166 offset:35840
	ds_read_b128 v[232:235], v166 offset:36864
	ds_read_b128 v[236:239], v166 offset:37888
	ds_read_b128 v[240:243], v166 offset:38912
	ds_read_b128 v[244:247], v166 offset:39936
	global_load_lds_dwordx4 v[202:203], off
	v_lshl_add_u64 v[202:203], s[46:47], 0, v[132:133]
	s_mov_b32 m0, s10
	s_nop 0
	global_load_lds_dwordx4 v[202:203], off
	s_waitcnt vmcnt(8)
	s_waitcnt lgkmcnt(0)
	s_setprio 1
	s_barrier
	v_mfma_f32_16x16x32_bf16 v[126:129], v[142:145], v[216:219], v[126:129]
	v_mfma_f32_16x16x32_bf16 v[122:125], v[172:175], v[216:219], v[122:125]
	v_mfma_f32_16x16x32_bf16 v[114:117], v[142:145], v[224:227], v[114:117]
	v_mfma_f32_16x16x32_bf16 v[106:109], v[172:175], v[224:227], v[106:109]
	v_mfma_f32_16x16x32_bf16 v[98:101], v[142:145], v[232:235], v[98:101]
	v_mfma_f32_16x16x32_bf16 v[90:93], v[172:175], v[232:235], v[90:93]
	v_mfma_f32_16x16x32_bf16 v[82:85], v[142:145], v[240:243], v[82:85]
	v_mfma_f32_16x16x32_bf16 v[74:77], v[172:175], v[240:243], v[74:77]
	v_mfma_f32_16x16x32_bf16 v[126:129], v[168:171], v[220:223], v[126:129]
	v_mfma_f32_16x16x32_bf16 v[122:125], v[176:179], v[220:223], v[122:125]
	v_mfma_f32_16x16x32_bf16 v[114:117], v[168:171], v[228:231], v[114:117]
	v_mfma_f32_16x16x32_bf16 v[106:109], v[176:179], v[228:231], v[106:109]
	v_mfma_f32_16x16x32_bf16 v[98:101], v[168:171], v[236:239], v[98:101]
	v_mfma_f32_16x16x32_bf16 v[90:93], v[176:179], v[236:239], v[90:93]
	v_mfma_f32_16x16x32_bf16 v[82:85], v[168:171], v[244:247], v[82:85]
	v_mfma_f32_16x16x32_bf16 v[74:77], v[176:179], v[244:247], v[74:77]
	s_setprio 0
	s_setprio 1
	v_mfma_f32_16x16x32_bf16 v[118:121], v[180:183], v[216:219], v[118:121]
	v_mfma_f32_16x16x32_bf16 v[110:113], v[188:191], v[216:219], v[110:113]
	v_mfma_f32_16x16x32_bf16 v[102:105], v[180:183], v[224:227], v[102:105]
	v_mfma_f32_16x16x32_bf16 v[94:97], v[188:191], v[224:227], v[94:97]
	v_mfma_f32_16x16x32_bf16 v[86:89], v[180:183], v[232:235], v[86:89]
	v_mfma_f32_16x16x32_bf16 v[78:81], v[188:191], v[232:235], v[78:81]
	v_mfma_f32_16x16x32_bf16 v[70:73], v[180:183], v[240:243], v[70:73]
	v_mfma_f32_16x16x32_bf16 v[66:69], v[188:191], v[240:243], v[66:69]
	v_mfma_f32_16x16x32_bf16 v[118:121], v[184:187], v[220:223], v[118:121]
	v_mfma_f32_16x16x32_bf16 v[110:113], v[204:207], v[220:223], v[110:113]
	v_mfma_f32_16x16x32_bf16 v[102:105], v[184:187], v[228:231], v[102:105]
	v_mfma_f32_16x16x32_bf16 v[94:97], v[204:207], v[228:231], v[94:97]
	v_mfma_f32_16x16x32_bf16 v[86:89], v[184:187], v[236:239], v[86:89]
	v_mfma_f32_16x16x32_bf16 v[78:81], v[204:207], v[236:239], v[78:81]
	v_mfma_f32_16x16x32_bf16 v[70:73], v[184:187], v[244:247], v[70:73]
	v_mfma_f32_16x16x32_bf16 v[66:69], v[204:207], v[244:247], v[66:69]
	s_barrier
; #define PG8_STAGE(bufoff, gbase, voff) do { _Pragma("unroll") for (int _i = 0; _i < 2; ++_i) \
;         __builtin_amdgcn_global_load_lds((const unsigned*)((const char*)(gbase) + (voff)[_i]), (PG8_LAS unsigned*)(lds + (bufoff) + ldsw + _i * 8192), 16, 0, 0); } while (0)
; #define PG8_LDA(dst, b, h) do { _Pragma("unroll") for (int m = 0; m < 4; ++m) _Pragma("unroll") for (int k = 0; k < 2; ++k) dst[m][k] = *(const PG8_LAS bf16x8*)(lds + PG8_SA(b, h) + aoff + m * 2048 + k * 1024); } while (0)
; #define PG8_MMA(ai, bj, At, Bt) do { __builtin_amdgcn_s_setprio(1); _Pragma("unroll") for (int m = 0; m < 4; ++m) _Pragma("unroll") for (int n = 0; n < 2; ++n) _Pragma("unroll") for (int k = 0; k < 2; ++k) \
;         acc[ai][bj][m][n] = __builtin_amdgcn_mfma_f32_16x16x32_bf16(Bt[n][k], At[m][k], acc[ai][bj][m][n], 0, 0, 0); __builtin_amdgcn_s_setprio(0); } while (0)
; #define PG8_WAIT_V(n) asm volatile("s_waitcnt vmcnt(" #n ")" ::: "memory")
; #define PG8_WAIT_L(n) asm volatile("s_waitcnt lgkmcnt(" #n ")" ::: "memory")
; #define PG8_BAR __builtin_amdgcn_s_barrier()
; #define PG8_SCHED __builtin_amdgcn_sched_barrier(0)
; template <class Epi, class Sched, bool ALIGN_EPI = false, bool SP2 = false>
; __device__ __forceinline__ void gemm_phase(PG8_LAS unsigned char* lds, const Gemm g, const Sched& S, const Epi& E) {
;     ...
;             PG8_LDA(At, 1, 1); PG8_STAGE(PG8_SB(1, 0), b3, voffB); PG8_STAGE(PG8_SB(1, 1), b3 + hstep, voffB); PG8_STAGE(PG8_SA(1, 0), a3, voffA);
;             PG8_WAIT_V(8); PG8_WAIT_L(0); PG8_BAR; PG8_MMA(1, 0, At, B0); PG8_MMA(1, 1, At, B1); PG8_BAR; PG8_SCHED;
;     ...
;         if constexpr (ALIGN_EPI) { if (wr == 0) PG8_BAR; }
	s_setprio 0
	s_add_i32 s46, s55, s0
	v_lshl_add_u64 v[192:193], v[192:193], 0, s[56:57]
	s_mov_b32 m0, s46
	ds_read_b128 v[216:219], v166 offset:49152
	ds_read_b128 v[220:223], v166 offset:50176
	ds_read_b128 v[224:227], v166 offset:51200
	ds_read_b128 v[228:231], v166 offset:52224
	ds_read_b128 v[232:235], v166 offset:53248
	ds_read_b128 v[236:239], v166 offset:54272
	ds_read_b128 v[240:243], v166 offset:55296
	ds_read_b128 v[244:247], v166 offset:56320
	global_load_lds_dwordx4 v[192:193], off
	s_add_i32 m0, s46, 0x2000
	s_add_u32 s44, s44, 0x80080
	v_lshl_add_u64 v[192:193], v[248:249], 0, s[56:57]
	s_addc_u32 s45, s45, 0
	s_add_i32 s46, s58, s0
	global_load_lds_dwordx4 v[192:193], off
	s_nop 0
	s_mov_b32 m0, s46
	s_nop 0
	global_load_lds_dwordx4 v0, s[44:45]
	s_nop 0
	s_add_i32 m0, s46, 0x2000
	s_nop 0
	global_load_lds_dwordx4 v130, s[44:45]
	v_lshl_add_u64 v[192:193], v[250:251], 0, s[56:57]
	s_mov_b32 m0, s11
	s_nop 0
	global_load_lds_dwordx4 v[192:193], off
	v_lshl_add_u64 v[192:193], v[200:201], 0, s[56:57]
	s_mov_b32 m0, s26
	s_nop 0
	global_load_lds_dwordx4 v[192:193], off
	s_waitcnt vmcnt(8)
	s_waitcnt lgkmcnt(0)
	s_setprio 1
	s_barrier
	v_mfma_f32_16x16x32_bf16 v[62:65], v[142:145], v[216:219], v[62:65]
	v_mfma_f32_16x16x32_bf16 v[58:61], v[172:175], v[216:219], v[58:61]
	v_mfma_f32_16x16x32_bf16 v[50:53], v[142:145], v[224:227], v[50:53]
	v_mfma_f32_16x16x32_bf16 v[42:45], v[172:175], v[224:227], v[42:45]
	v_mfma_f32_16x16x32_bf16 v[34:37], v[142:145], v[232:235], v[34:37]
	v_mfma_f32_16x16x32_bf16 v[26:29], v[172:175], v[232:235], v[26:29]
	v_mfma_f32_16x16x32_bf16 v[18:21], v[142:145], v[240:243], v[18:21]
	v_mfma_f32_16x16x32_bf16 v[10:13], v[172:175], v[240:243], v[10:13]
	v_mfma_f32_16x16x32_bf16 v[62:65], v[168:171], v[220:223], v[62:65]
	v_mfma_f32_16x16x32_bf16 v[58:61], v[176:179], v[220:223], v[58:61]
	v_mfma_f32_16x16x32_bf16 v[50:53], v[168:171], v[228:231], v[50:53]
	v_mfma_f32_16x16x32_bf16 v[42:45], v[176:179], v[228:231], v[42:45]
	v_mfma_f32_16x16x32_bf16 v[34:37], v[168:171], v[236:239], v[34:37]
	v_mfma_f32_16x16x32_bf16 v[26:29], v[176:179], v[236:239], v[26:29]
	v_mfma_f32_16x16x32_bf16 v[18:21], v[168:171], v[244:247], v[18:21]
	v_mfma_f32_16x16x32_bf16 v[10:13], v[176:179], v[244:247], v[10:13]
	s_setprio 0
	s_setprio 1
	v_mfma_f32_16x16x32_bf16 v[54:57], v[180:183], v[216:219], v[54:57]
	v_mfma_f32_16x16x32_bf16 v[46:49], v[188:191], v[216:219], v[46:49]
	v_mfma_f32_16x16x32_bf16 v[38:41], v[180:183], v[224:227], v[38:41]
	v_mfma_f32_16x16x32_bf16 v[30:33], v[188:191], v[224:227], v[30:33]
	v_mfma_f32_16x16x32_bf16 v[22:25], v[180:183], v[232:235], v[22:25]
	v_mfma_f32_16x16x32_bf16 v[14:17], v[188:191], v[232:235], v[14:17]
	v_mfma_f32_16x16x32_bf16 v[6:9], v[180:183], v[240:243], v[6:9]
	v_mfma_f32_16x16x32_bf16 v[2:5], v[188:191], v[240:243], v[2:5]
	v_mfma_f32_16x16x32_bf16 v[54:57], v[184:187], v[220:223], v[54:57]
	v_mfma_f32_16x16x32_bf16 v[46:49], v[204:207], v[220:223], v[46:49]
	v_mfma_f32_16x16x32_bf16 v[38:41], v[184:187], v[228:231], v[38:41]
	v_mfma_f32_16x16x32_bf16 v[30:33], v[204:207], v[228:231], v[30:33]
	v_mfma_f32_16x16x32_bf16 v[22:25], v[184:187], v[236:239], v[22:25]
	v_mfma_f32_16x16x32_bf16 v[14:17], v[204:207], v[236:239], v[14:17]
	v_mfma_f32_16x16x32_bf16 v[6:9], v[184:187], v[244:247], v[6:9]
	v_mfma_f32_16x16x32_bf16 v[2:5], v[204:207], v[244:247], v[2:5]
	s_barrier
	s_setprio 0
	s_add_i32 s54, s54, 2
	s_add_u32 s24, s24, 0x100
	s_addc_u32 s25, s25, 0
	s_add_u32 s50, s50, 0x100
	s_addc_u32 s51, s51, 0
	s_cmp_gt_u32 s54, 29
	s_cbranch_scc0 .LBB0_146
	s_and_b64 vcc, exec, s[16:17]
	s_cbranch_vccz .LBB0_149
	s_barrier

; #define PG8_STAGE(bufoff, gbase, voff) do { _Pragma("unroll") for (int _i = 0; _i < 2; ++_i) \
;         __builtin_amdgcn_global_load_lds((const unsigned*)((const char*)(gbase) + (voff)[_i]), (PG8_LAS unsigned*)(lds + (bufoff) + ldsw + _i * 8192), 16, 0, 0); } while (0)
; #define PG8_LDA(dst, b, h) do { _Pragma("unroll") for (int m = 0; m < 4; ++m) _Pragma("unroll") for (int k = 0; k < 2; ++k) dst[m][k] = *(const PG8_LAS bf16x8*)(lds + PG8_SA(b, h) + aoff + m * 2048 + k * 1024); } while (0)
; #define PG8_LDB(dst, b, h) do { _Pragma("unroll") for (int n = 0; n < 2; ++n) _Pragma("unroll") for (int k = 0; k < 2; ++k) dst[n][k] = *(const PG8_LAS bf16x8*)(lds + PG8_SB(b, h) + boff + n * 2048 + k * 1024); } while (0)
; #define PG8_MMA(ai, bj, At, Bt) do { __builtin_amdgcn_s_setprio(1); _Pragma("unroll") for (int m = 0; m < 4; ++m) _Pragma("unroll") for (int n = 0; n < 2; ++n) _Pragma("unroll") for (int k = 0; k < 2; ++k) \
;         acc[ai][bj][m][n] = __builtin_amdgcn_mfma_f32_16x16x32_bf16(Bt[n][k], At[m][k], acc[ai][bj][m][n], 0, 0, 0); __builtin_amdgcn_s_setprio(0); } while (0)
; #define PG8_WAIT_V(n) asm volatile("s_waitcnt vmcnt(" #n ")" ::: "memory")
; #define PG8_BAR __builtin_amdgcn_s_barrier()
; template <class Epi, class Sched, bool ALIGN_EPI = false, bool SP2 = false>
; __device__ __forceinline__ void gemm_phase(PG8_LAS unsigned char* lds, const Gemm g, const Sched& S, const Epi& E) {
;     ...
;         for (int t = 0; t < nt; t += 2) {
;             const bool last = (t == nt - 2);
;             const char* a1 = cA + (size_t)(t + 1) * kstep;
;             const char* a2 = last ? nA : cA + (size_t)(t + 2) * kstep; const char* b2 = last ? nB : cB + (size_t)(t + 2) * kstep;
;             const char* a3 = a2 + kstep; const char* b3 = b2 + kstep;
;             if (last && has_next) S.a_ready(nxt);
;             if constexpr (SP2) {
;             PG8_LDB(B0, 0, 0); PG8_LDB(B1, 0, 1); PG8_SCHED; PG8_LDA(At, 0, 0); PG8_STAGE(PG8_SA(1, 1), a1 + hstep, voffA);
;             PG8_WAIT_V(8); PG8_WAIT_L(0); PG8_BAR; PG8_MMA(0, 0, At, B0); PG8_MMA(0, 1, At, B1); PG8_BAR; PG8_SCHED;
;             PG8_LDA(At, 0, 1); PG8_STAGE(PG8_SB(0, 0), b2, voffB); PG8_STAGE(PG8_SB(0, 1), b2 + hstep, voffB); PG8_STAGE(PG8_SA(0, 0), a2, voffA);
;             PG8_WAIT_V(8); PG8_WAIT_L(0); PG8_BAR; PG8_MMA(1, 0, At, B0); PG8_MMA(1, 1, At, B1); PG8_BAR; PG8_SCHED;
.LBB0_489:
	s_add_u32 s50, s24, 0xfff80080
	s_addc_u32 s51, s25, -1
	s_add_i32 s66, 0, 0x10000
	s_cmp_eq_u32 s63, 28
	s_cselect_b32 s59, s15, s51
	s_cselect_b32 s58, s23, s50
	s_cselect_b32 s51, s21, s62
	s_cselect_b32 s50, s26, s27
	s_add_i32 s68, 0, 0x14000
	v_add_u32_e32 v152, s66, v163
	v_add_u32_e32 v160, s68, v163
	ds_read_b128 v[130:133], v152
	ds_read_b128 v[134:137], v152 offset:1024
	ds_read_b128 v[138:141], v152 offset:2048
	ds_read_b128 v[152:155], v152 offset:3072
	ds_read_b128 v[156:159], v160
	ds_read_b128 v[166:169], v160 offset:1024
	ds_read_b128 v[170:173], v160 offset:2048
	ds_read_b128 v[174:177], v160 offset:3072
	v_lshl_add_u64 v[160:161], s[24:25], 0, v[148:149]
	s_add_i32 m0, s3, 0xc000
	ds_read_b128 v[178:181], v165
	ds_read_b128 v[182:185], v165 offset:1024
	ds_read_b128 v[186:189], v165 offset:2048
	ds_read_b128 v[190:193], v165 offset:3072
	ds_read_b128 v[204:207], v165 offset:4096
	ds_read_b128 v[218:221], v165 offset:5120
	ds_read_b128 v[222:225], v165 offset:6144
	ds_read_b128 v[226:229], v165 offset:7168
	global_load_lds_dwordx4 v[160:161], off
	s_nop 0
	s_add_i32 m0, s3, 0xe000
	s_nop 0
	global_load_lds_dwordx4 v150, s[24:25]
	s_waitcnt vmcnt(8)
	s_waitcnt lgkmcnt(0)
	s_setprio 1
	s_barrier
	v_mfma_f32_16x16x32_bf16 v[126:129], v[130:133], v[178:181], v[126:129]
	v_mfma_f32_16x16x32_bf16 v[122:125], v[138:141], v[178:181], v[122:125]
	v_mfma_f32_16x16x32_bf16 v[110:113], v[130:133], v[186:189], v[110:113]
	v_mfma_f32_16x16x32_bf16 v[106:109], v[138:141], v[186:189], v[106:109]
	v_mfma_f32_16x16x32_bf16 v[94:97], v[130:133], v[204:207], v[94:97]
	v_mfma_f32_16x16x32_bf16 v[90:93], v[138:141], v[204:207], v[90:93]
	v_mfma_f32_16x16x32_bf16 v[78:81], v[130:133], v[222:225], v[78:81]
	v_mfma_f32_16x16x32_bf16 v[74:77], v[138:141], v[222:225], v[74:77]
	v_mfma_f32_16x16x32_bf16 v[126:129], v[134:137], v[182:185], v[126:129]
	v_mfma_f32_16x16x32_bf16 v[122:125], v[152:155], v[182:185], v[122:125]
	v_mfma_f32_16x16x32_bf16 v[110:113], v[134:137], v[190:193], v[110:113]
	v_mfma_f32_16x16x32_bf16 v[106:109], v[152:155], v[190:193], v[106:109]
	v_mfma_f32_16x16x32_bf16 v[94:97], v[134:137], v[218:221], v[94:97]
	v_mfma_f32_16x16x32_bf16 v[90:93], v[152:155], v[218:221], v[90:93]
	v_mfma_f32_16x16x32_bf16 v[78:81], v[134:137], v[226:229], v[78:81]
	v_mfma_f32_16x16x32_bf16 v[74:77], v[152:155], v[226:229], v[74:77]
	s_setprio 0
	s_setprio 1
	v_mfma_f32_16x16x32_bf16 v[118:121], v[156:159], v[178:181], v[118:121]
	v_mfma_f32_16x16x32_bf16 v[114:117], v[170:173], v[178:181], v[114:117]
	v_mfma_f32_16x16x32_bf16 v[102:105], v[156:159], v[186:189], v[102:105]
	v_mfma_f32_16x16x32_bf16 v[98:101], v[170:173], v[186:189], v[98:101]
	v_mfma_f32_16x16x32_bf16 v[86:89], v[156:159], v[204:207], v[86:89]
	v_mfma_f32_16x16x32_bf16 v[82:85], v[170:173], v[204:207], v[82:85]
	v_mfma_f32_16x16x32_bf16 v[70:73], v[156:159], v[222:225], v[70:73]
	v_mfma_f32_16x16x32_bf16 v[66:69], v[170:173], v[222:225], v[66:69]
	v_mfma_f32_16x16x32_bf16 v[118:121], v[166:169], v[182:185], v[118:121]
	v_mfma_f32_16x16x32_bf16 v[114:117], v[174:177], v[182:185], v[114:117]
	v_mfma_f32_16x16x32_bf16 v[102:105], v[166:169], v[190:193], v[102:105]
	v_mfma_f32_16x16x32_bf16 v[98:101], v[174:177], v[190:193], v[98:101]
	v_mfma_f32_16x16x32_bf16 v[86:89], v[166:169], v[218:221], v[86:89]
	v_mfma_f32_16x16x32_bf16 v[82:85], v[174:177], v[218:221], v[82:85]
	v_mfma_f32_16x16x32_bf16 v[70:73], v[166:169], v[226:229], v[70:73]
	v_mfma_f32_16x16x32_bf16 v[66:69], v[174:177], v[226:229], v[66:69]
	s_barrier
	s_setprio 0
	s_add_i32 s66, s66, s2
	v_lshl_add_u64 v[160:161], s[50:51], 0, v[0:1]
	s_mov_b32 m0, s66
	ds_read_b128 v[178:181], v165 offset:16384
	ds_read_b128 v[182:185], v165 offset:17408
	ds_read_b128 v[186:189], v165 offset:18432
	ds_read_b128 v[190:193], v165 offset:19456
	ds_read_b128 v[204:207], v165 offset:20480
	ds_read_b128 v[218:221], v165 offset:21504
	ds_read_b128 v[222:225], v165 offset:22528
	ds_read_b128 v[226:229], v165 offset:23552
	global_load_lds_dwordx4 v[160:161], off
	s_add_i32 m0, s66, 0x2000
	s_add_u32 s66, s50, 0x80000
	v_lshl_add_u64 v[200:201], s[50:51], 0, v[146:147]
	s_addc_u32 s67, s51, 0
	s_add_i32 s68, s68, s2
	global_load_lds_dwordx4 v[200:201], off
	s_nop 0
	s_mov_b32 m0, s68
	v_lshl_add_u64 v[230:231], s[58:59], 0, v[144:145]
	global_load_lds_dwordx4 v0, s[66:67]
	s_nop 0
	s_add_i32 m0, s68, 0x2000
	s_nop 0
	global_load_lds_dwordx4 v146, s[66:67]
	v_lshl_add_u64 v[202:203], s[58:59], 0, v[142:143]
	s_mov_b32 m0, s3
	s_nop 0
	global_load_lds_dwordx4 v[202:203], off
	s_mov_b32 m0, s10
	s_nop 0
	global_load_lds_dwordx4 v[230:231], off
	s_waitcnt vmcnt(8)
	s_waitcnt lgkmcnt(0)
	s_setprio 1
	s_barrier
; #define PG8_STAGE(bufoff, gbase, voff) do { _Pragma("unroll") for (int _i = 0; _i < 2; ++_i) \
;         __builtin_amdgcn_global_load_lds((const unsigned*)((const char*)(gbase) + (voff)[_i]), (PG8_LAS unsigned*)(lds + (bufoff) + ldsw + _i * 8192), 16, 0, 0); } while (0)
; #define PG8_LDA(dst, b, h) do { _Pragma("unroll") for (int m = 0; m < 4; ++m) _Pragma("unroll") for (int k = 0; k < 2; ++k) dst[m][k] = *(const PG8_LAS bf16x8*)(lds + PG8_SA(b, h) + aoff + m * 2048 + k * 1024); } while (0)
; #define PG8_LDB(dst, b, h) do { _Pragma("unroll") for (int n = 0; n < 2; ++n) _Pragma("unroll") for (int k = 0; k < 2; ++k) dst[n][k] = *(const PG8_LAS bf16x8*)(lds + PG8_SB(b, h) + boff + n * 2048 + k * 1024); } while (0)
; #define PG8_MMA(ai, bj, At, Bt) do { __builtin_amdgcn_s_setprio(1); _Pragma("unroll") for (int m = 0; m < 4; ++m) _Pragma("unroll") for (int n = 0; n < 2; ++n) _Pragma("unroll") for (int k = 0; k < 2; ++k) \
;         acc[ai][bj][m][n] = __builtin_amdgcn_mfma_f32_16x16x32_bf16(Bt[n][k], At[m][k], acc[ai][bj][m][n], 0, 0, 0); __builtin_amdgcn_s_setprio(0); } while (0)
; #define PG8_WAIT_V(n) asm volatile("s_waitcnt vmcnt(" #n ")" ::: "memory")
; #define PG8_WAIT_L(n) asm volatile("s_waitcnt lgkmcnt(" #n ")" ::: "memory")
; #define PG8_BAR __builtin_amdgcn_s_barrier()
; #define PG8_SCHED __builtin_amdgcn_sched_barrier(0)
; template <class Epi, class Sched, bool ALIGN_EPI = false, bool SP2 = false>
; __device__ __forceinline__ void gemm_phase(PG8_LAS unsigned char* lds, const Gemm g, const Sched& S, const Epi& E) {
;     ...
;             PG8_WAIT_V(8); PG8_WAIT_L(0); PG8_BAR; PG8_MMA(1, 0, At, B0); PG8_MMA(1, 1, At, B1); PG8_BAR; PG8_SCHED;
;             PG8_LDB(B0, 1, 0); PG8_LDB(B1, 1, 1); PG8_SCHED; PG8_LDA(At, 1, 0); PG8_STAGE(PG8_SA(0, 1), a2 + hstep, voffA);
;             PG8_WAIT_V(8); PG8_WAIT_L(0); PG8_BAR; PG8_MMA(0, 0, At, B0); PG8_MMA(0, 1, At, B1); PG8_BAR; PG8_SCHED;
;             PG8_LDA(At, 1, 1); PG8_STAGE(PG8_SB(1, 0), b3, voffB); PG8_STAGE(PG8_SB(1, 1), b3 + hstep, voffB); PG8_STAGE(PG8_SA(1, 0), a3, voffA);
	v_mfma_f32_16x16x32_bf16 v[62:65], v[130:133], v[178:181], v[62:65]
	v_mfma_f32_16x16x32_bf16 v[58:61], v[138:141], v[178:181], v[58:61]
	v_mfma_f32_16x16x32_bf16 v[46:49], v[130:133], v[186:189], v[46:49]
	v_mfma_f32_16x16x32_bf16 v[42:45], v[138:141], v[186:189], v[42:45]
	v_mfma_f32_16x16x32_bf16 v[30:33], v[130:133], v[204:207], v[30:33]
	v_mfma_f32_16x16x32_bf16 v[26:29], v[138:141], v[204:207], v[26:29]
	v_mfma_f32_16x16x32_bf16 v[14:17], v[130:133], v[222:225], v[14:17]
	v_mfma_f32_16x16x32_bf16 v[10:13], v[138:141], v[222:225], v[10:13]
	v_mfma_f32_16x16x32_bf16 v[62:65], v[134:137], v[182:185], v[62:65]
	v_mfma_f32_16x16x32_bf16 v[58:61], v[152:155], v[182:185], v[58:61]
	v_mfma_f32_16x16x32_bf16 v[46:49], v[134:137], v[190:193], v[46:49]
	v_mfma_f32_16x16x32_bf16 v[42:45], v[152:155], v[190:193], v[42:45]
	v_mfma_f32_16x16x32_bf16 v[30:33], v[134:137], v[218:221], v[30:33]
	v_mfma_f32_16x16x32_bf16 v[26:29], v[152:155], v[218:221], v[26:29]
	v_mfma_f32_16x16x32_bf16 v[14:17], v[134:137], v[226:229], v[14:17]
	v_mfma_f32_16x16x32_bf16 v[10:13], v[152:155], v[226:229], v[10:13]
	s_setprio 0
	s_setprio 1
	v_mfma_f32_16x16x32_bf16 v[54:57], v[156:159], v[178:181], v[54:57]
	v_mfma_f32_16x16x32_bf16 v[50:53], v[170:173], v[178:181], v[50:53]
	v_mfma_f32_16x16x32_bf16 v[38:41], v[156:159], v[186:189], v[38:41]
	v_mfma_f32_16x16x32_bf16 v[34:37], v[170:173], v[186:189], v[34:37]
	v_mfma_f32_16x16x32_bf16 v[22:25], v[156:159], v[204:207], v[22:25]
	v_mfma_f32_16x16x32_bf16 v[18:21], v[170:173], v[204:207], v[18:21]
	v_mfma_f32_16x16x32_bf16 v[6:9], v[156:159], v[222:225], v[6:9]
	v_mfma_f32_16x16x32_bf16 v[2:5], v[170:173], v[222:225], v[2:5]
	v_mfma_f32_16x16x32_bf16 v[54:57], v[166:169], v[182:185], v[54:57]
	v_mfma_f32_16x16x32_bf16 v[50:53], v[174:177], v[182:185], v[50:53]
	v_mfma_f32_16x16x32_bf16 v[38:41], v[166:169], v[190:193], v[38:41]
	v_mfma_f32_16x16x32_bf16 v[34:37], v[174:177], v[190:193], v[34:37]
	v_mfma_f32_16x16x32_bf16 v[22:25], v[166:169], v[218:221], v[22:25]
	v_mfma_f32_16x16x32_bf16 v[18:21], v[174:177], v[218:221], v[18:21]
	v_mfma_f32_16x16x32_bf16 v[6:9], v[166:169], v[226:229], v[6:9]
	v_mfma_f32_16x16x32_bf16 v[2:5], v[174:177], v[226:229], v[2:5]
	s_barrier
	s_setprio 0
	s_add_i32 s66, 0, 0x18000
	s_add_i32 s67, 0, 0x1c000
	v_add_u32_e32 v152, s66, v163
	v_add_u32_e32 v174, s67, v163
	ds_read_b128 v[130:133], v152
	ds_read_b128 v[134:137], v152 offset:1024
	ds_read_b128 v[138:141], v152 offset:2048
	ds_read_b128 v[152:155], v152 offset:3072
	ds_read_b128 v[156:159], v174
	ds_read_b128 v[166:169], v174 offset:1024
	ds_read_b128 v[170:173], v174 offset:2048
	ds_read_b128 v[174:177], v174 offset:3072
	s_add_u32 s58, s58, 0x80000
	s_addc_u32 s59, s59, 0
	s_mov_b32 m0, s11
	v_lshl_add_u64 v[232:233], s[58:59], 0, v[142:143]
	ds_read_b128 v[178:181], v165 offset:32768
	ds_read_b128 v[182:185], v165 offset:33792
	ds_read_b128 v[186:189], v165 offset:34816
	ds_read_b128 v[190:193], v165 offset:35840
	ds_read_b128 v[204:207], v165 offset:36864
	ds_read_b128 v[218:221], v165 offset:37888
	ds_read_b128 v[222:225], v165 offset:38912
	ds_read_b128 v[226:229], v165 offset:39936
	global_load_lds_dwordx4 v[232:233], off
	v_lshl_add_u64 v[232:233], s[58:59], 0, v[144:145]
	s_mov_b32 m0, s33
	s_nop 0
	global_load_lds_dwordx4 v[232:233], off
	s_waitcnt vmcnt(8)
	s_waitcnt lgkmcnt(0)
	s_setprio 1
	s_barrier
	v_mfma_f32_16x16x32_bf16 v[126:129], v[130:133], v[178:181], v[126:129]
	v_mfma_f32_16x16x32_bf16 v[122:125], v[138:141], v[178:181], v[122:125]
	v_mfma_f32_16x16x32_bf16 v[110:113], v[130:133], v[186:189], v[110:113]
	v_mfma_f32_16x16x32_bf16 v[106:109], v[138:141], v[186:189], v[106:109]
	v_mfma_f32_16x16x32_bf16 v[94:97], v[130:133], v[204:207], v[94:97]
	v_mfma_f32_16x16x32_bf16 v[90:93], v[138:141], v[204:207], v[90:93]
	v_mfma_f32_16x16x32_bf16 v[78:81], v[130:133], v[222:225], v[78:81]
	v_mfma_f32_16x16x32_bf16 v[74:77], v[138:141], v[222:225], v[74:77]
	v_mfma_f32_16x16x32_bf16 v[126:129], v[134:137], v[182:185], v[126:129]
	v_mfma_f32_16x16x32_bf16 v[122:125], v[152:155], v[182:185], v[122:125]
	v_mfma_f32_16x16x32_bf16 v[110:113], v[134:137], v[190:193], v[110:113]
	v_mfma_f32_16x16x32_bf16 v[106:109], v[152:155], v[190:193], v[106:109]
	v_mfma_f32_16x16x32_bf16 v[94:97], v[134:137], v[218:221], v[94:97]
	v_mfma_f32_16x16x32_bf16 v[90:93], v[152:155], v[218:221], v[90:93]
	v_mfma_f32_16x16x32_bf16 v[78:81], v[134:137], v[226:229], v[78:81]
	v_mfma_f32_16x16x32_bf16 v[74:77], v[152:155], v[226:229], v[74:77]
	s_setprio 0
	s_setprio 1
	v_mfma_f32_16x16x32_bf16 v[118:121], v[156:159], v[178:181], v[118:121]
	v_mfma_f32_16x16x32_bf16 v[114:117], v[170:173], v[178:181], v[114:117]
	v_mfma_f32_16x16x32_bf16 v[102:105], v[156:159], v[186:189], v[102:105]
	v_mfma_f32_16x16x32_bf16 v[98:101], v[170:173], v[186:189], v[98:101]
	v_mfma_f32_16x16x32_bf16 v[86:89], v[156:159], v[204:207], v[86:89]
	v_mfma_f32_16x16x32_bf16 v[82:85], v[170:173], v[204:207], v[82:85]
	v_mfma_f32_16x16x32_bf16 v[70:73], v[156:159], v[222:225], v[70:73]
	v_mfma_f32_16x16x32_bf16 v[66:69], v[170:173], v[222:225], v[66:69]
	v_mfma_f32_16x16x32_bf16 v[118:121], v[166:169], v[182:185], v[118:121]
	v_mfma_f32_16x16x32_bf16 v[114:117], v[174:177], v[182:185], v[114:117]
	v_mfma_f32_16x16x32_bf16 v[102:105], v[166:169], v[190:193], v[102:105]
	v_mfma_f32_16x16x32_bf16 v[98:101], v[174:177], v[190:193], v[98:101]
	v_mfma_f32_16x16x32_bf16 v[86:89], v[166:169], v[218:221], v[86:89]
	v_mfma_f32_16x16x32_bf16 v[82:85], v[174:177], v[218:221], v[82:85]
	v_mfma_f32_16x16x32_bf16 v[70:73], v[166:169], v[226:229], v[70:73]
	v_mfma_f32_16x16x32_bf16 v[66:69], v[174:177], v[226:229], v[66:69]
	s_barrier
; #define PG8_STAGE(bufoff, gbase, voff) do { _Pragma("unroll") for (int _i = 0; _i < 2; ++_i) \
;         __builtin_amdgcn_global_load_lds((const unsigned*)((const char*)(gbase) + (voff)[_i]), (PG8_LAS unsigned*)(lds + (bufoff) + ldsw + _i * 8192), 16, 0, 0); } while (0)
; #define PG8_LDA(dst, b, h) do { _Pragma("unroll") for (int m = 0; m < 4; ++m) _Pragma("unroll") for (int k = 0; k < 2; ++k) dst[m][k] = *(const PG8_LAS bf16x8*)(lds + PG8_SA(b, h) + aoff + m * 2048 + k * 1024); } while (0)
; #define PG8_MMA(ai, bj, At, Bt) do { __builtin_amdgcn_s_setprio(1); _Pragma("unroll") for (int m = 0; m < 4; ++m) _Pragma("unroll") for (int n = 0; n < 2; ++n) _Pragma("unroll") for (int k = 0; k < 2; ++k) \
;         acc[ai][bj][m][n] = __builtin_amdgcn_mfma_f32_16x16x32_bf16(Bt[n][k], At[m][k], acc[ai][bj][m][n], 0, 0, 0); __builtin_amdgcn_s_setprio(0); } while (0)
; #define PG8_WAIT_V(n) asm volatile("s_waitcnt vmcnt(" #n ")" ::: "memory")
; #define PG8_WAIT_L(n) asm volatile("s_waitcnt lgkmcnt(" #n ")" ::: "memory")
; #define PG8_BAR __builtin_amdgcn_s_barrier()
; #define PG8_SCHED __builtin_amdgcn_sched_barrier(0)
; template <class Epi, class Sched, bool ALIGN_EPI = false, bool SP2 = false>
; __device__ __forceinline__ void gemm_phase(PG8_LAS unsigned char* lds, const Gemm g, const Sched& S, const Epi& E) {
;     ...
;             PG8_LDA(At, 1, 1); PG8_STAGE(PG8_SB(1, 0), b3, voffB); PG8_STAGE(PG8_SB(1, 1), b3 + hstep, voffB); PG8_STAGE(PG8_SA(1, 0), a3, voffA);
;             PG8_WAIT_V(8); PG8_WAIT_L(0); PG8_BAR; PG8_MMA(1, 0, At, B0); PG8_MMA(1, 1, At, B1); PG8_BAR; PG8_SCHED;
;     ...
;         if constexpr (ALIGN_EPI) { if (wr == 0) PG8_BAR; }
	s_setprio 0
	s_add_i32 s58, s66, s2
	v_lshl_add_u64 v[160:161], v[160:161], 0, s[56:57]
	s_mov_b32 m0, s58
	ds_read_b128 v[178:181], v165 offset:49152
	ds_read_b128 v[182:185], v165 offset:50176
	ds_read_b128 v[186:189], v165 offset:51200
	ds_read_b128 v[190:193], v165 offset:52224
	ds_read_b128 v[204:207], v165 offset:53248
	ds_read_b128 v[218:221], v165 offset:54272
	ds_read_b128 v[222:225], v165 offset:55296
	ds_read_b128 v[226:229], v165 offset:56320
	global_load_lds_dwordx4 v[160:161], off
	s_add_i32 m0, s58, 0x2000
	s_add_u32 s50, s50, 0x80080
	v_lshl_add_u64 v[160:161], v[200:201], 0, s[56:57]
	s_addc_u32 s51, s51, 0
	s_add_i32 s58, s67, s2
	global_load_lds_dwordx4 v[160:161], off
	s_nop 0
	s_mov_b32 m0, s58
	s_nop 0
	global_load_lds_dwordx4 v0, s[50:51]
	s_nop 0
	s_add_i32 m0, s58, 0x2000
	s_nop 0
	global_load_lds_dwordx4 v146, s[50:51]
	v_lshl_add_u64 v[160:161], v[202:203], 0, s[56:57]
	s_mov_b32 m0, s49
	s_nop 0
	global_load_lds_dwordx4 v[160:161], off
	v_lshl_add_u64 v[160:161], v[230:231], 0, s[56:57]
	s_mov_b32 m0, s54
	s_nop 0
	global_load_lds_dwordx4 v[160:161], off
	s_waitcnt vmcnt(8)
	s_waitcnt lgkmcnt(0)
	s_setprio 1
	s_barrier
	v_mfma_f32_16x16x32_bf16 v[62:65], v[130:133], v[178:181], v[62:65]
	v_mfma_f32_16x16x32_bf16 v[58:61], v[138:141], v[178:181], v[58:61]
	v_mfma_f32_16x16x32_bf16 v[46:49], v[130:133], v[186:189], v[46:49]
	v_mfma_f32_16x16x32_bf16 v[42:45], v[138:141], v[186:189], v[42:45]
	v_mfma_f32_16x16x32_bf16 v[30:33], v[130:133], v[204:207], v[30:33]
	v_mfma_f32_16x16x32_bf16 v[26:29], v[138:141], v[204:207], v[26:29]
	v_mfma_f32_16x16x32_bf16 v[14:17], v[130:133], v[222:225], v[14:17]
	v_mfma_f32_16x16x32_bf16 v[10:13], v[138:141], v[222:225], v[10:13]
	v_mfma_f32_16x16x32_bf16 v[62:65], v[134:137], v[182:185], v[62:65]
	v_mfma_f32_16x16x32_bf16 v[58:61], v[152:155], v[182:185], v[58:61]
	v_mfma_f32_16x16x32_bf16 v[46:49], v[134:137], v[190:193], v[46:49]
	v_mfma_f32_16x16x32_bf16 v[42:45], v[152:155], v[190:193], v[42:45]
	v_mfma_f32_16x16x32_bf16 v[30:33], v[134:137], v[218:221], v[30:33]
	v_mfma_f32_16x16x32_bf16 v[26:29], v[152:155], v[218:221], v[26:29]
	v_mfma_f32_16x16x32_bf16 v[14:17], v[134:137], v[226:229], v[14:17]
	v_mfma_f32_16x16x32_bf16 v[10:13], v[152:155], v[226:229], v[10:13]
	s_setprio 0
	s_setprio 1
	v_mfma_f32_16x16x32_bf16 v[54:57], v[156:159], v[178:181], v[54:57]
	v_mfma_f32_16x16x32_bf16 v[50:53], v[170:173], v[178:181], v[50:53]
	v_mfma_f32_16x16x32_bf16 v[38:41], v[156:159], v[186:189], v[38:41]
	v_mfma_f32_16x16x32_bf16 v[34:37], v[170:173], v[186:189], v[34:37]
	v_mfma_f32_16x16x32_bf16 v[22:25], v[156:159], v[204:207], v[22:25]
	v_mfma_f32_16x16x32_bf16 v[18:21], v[170:173], v[204:207], v[18:21]
	v_mfma_f32_16x16x32_bf16 v[6:9], v[156:159], v[222:225], v[6:9]
	v_mfma_f32_16x16x32_bf16 v[2:5], v[170:173], v[222:225], v[2:5]
	v_mfma_f32_16x16x32_bf16 v[54:57], v[166:169], v[182:185], v[54:57]
	v_mfma_f32_16x16x32_bf16 v[50:53], v[174:177], v[182:185], v[50:53]
	v_mfma_f32_16x16x32_bf16 v[38:41], v[166:169], v[190:193], v[38:41]
	v_mfma_f32_16x16x32_bf16 v[34:37], v[174:177], v[190:193], v[34:37]
	v_mfma_f32_16x16x32_bf16 v[22:25], v[166:169], v[218:221], v[22:25]
	v_mfma_f32_16x16x32_bf16 v[18:21], v[174:177], v[218:221], v[18:21]
	v_mfma_f32_16x16x32_bf16 v[6:9], v[166:169], v[226:229], v[6:9]
	v_mfma_f32_16x16x32_bf16 v[2:5], v[174:177], v[226:229], v[2:5]
	s_barrier
	s_setprio 0
	s_add_i32 s63, s63, 2
	s_add_u32 s24, s24, 0x100
	s_addc_u32 s25, s25, 0
	s_add_u32 s27, s27, 0x100
	s_addc_u32 s62, s62, 0
	s_cmp_gt_u32 s63, 29
	s_cbranch_scc0 .LBB0_489
	s_and_b64 vcc, exec, s[18:19]
	s_cbranch_vccz .LBB0_492
	s_barrier

; #define PG8_STAGE(bufoff, gbase, voff) do { _Pragma("unroll") for (int _i = 0; _i < 2; ++_i) \
;         __builtin_amdgcn_global_load_lds((const unsigned*)((const char*)(gbase) + (voff)[_i]), (PG8_LAS unsigned*)(lds + (bufoff) + ldsw + _i * 8192), 16, 0, 0); } while (0)
; #define PG8_LDA(dst, b, h) do { _Pragma("unroll") for (int m = 0; m < 4; ++m) _Pragma("unroll") for (int k = 0; k < 2; ++k) dst[m][k] = *(const PG8_LAS bf16x8*)(lds + PG8_SA(b, h) + aoff + m * 2048 + k * 1024); } while (0)
; #define PG8_LDB(dst, b, h) do { _Pragma("unroll") for (int n = 0; n < 2; ++n) _Pragma("unroll") for (int k = 0; k < 2; ++k) dst[n][k] = *(const PG8_LAS bf16x8*)(lds + PG8_SB(b, h) + boff + n * 2048 + k * 1024); } while (0)
; #define PG8_MMA(ai, bj, At, Bt) do { __builtin_amdgcn_s_setprio(1); _Pragma("unroll") for (int m = 0; m < 4; ++m) _Pragma("unroll") for (int n = 0; n < 2; ++n) _Pragma("unroll") for (int k = 0; k < 2; ++k) \
;         acc[ai][bj][m][n] = __builtin_amdgcn_mfma_f32_16x16x32_bf16(Bt[n][k], At[m][k], acc[ai][bj][m][n], 0, 0, 0); __builtin_amdgcn_s_setprio(0); } while (0)
; #define PG8_WAIT_V(n) asm volatile("s_waitcnt vmcnt(" #n ")" ::: "memory")
; #define PG8_BAR __builtin_amdgcn_s_barrier()
; template <class Epi, class Sched, bool ALIGN_EPI = false, bool SP2 = false>
; __device__ __forceinline__ void gemm_phase(PG8_LAS unsigned char* lds, const Gemm g, const Sched& S, const Epi& E) {
;     ...
;         for (int t = 0; t < nt; t += 2) {
;             const bool last = (t == nt - 2);
;             const char* a1 = cA + (size_t)(t + 1) * kstep;
;             const char* a2 = last ? nA : cA + (size_t)(t + 2) * kstep; const char* b2 = last ? nB : cB + (size_t)(t + 2) * kstep;
;             const char* a3 = a2 + kstep; const char* b3 = b2 + kstep;
;             if (last && has_next) S.a_ready(nxt);
;             if constexpr (SP2) {
;             PG8_LDB(B0, 0, 0); PG8_LDB(B1, 0, 1); PG8_SCHED; PG8_LDA(At, 0, 0); PG8_STAGE(PG8_SA(1, 1), a1 + hstep, voffA);
;             PG8_WAIT_V(8); PG8_WAIT_L(0); PG8_BAR; PG8_MMA(0, 0, At, B0); PG8_MMA(0, 1, At, B1); PG8_BAR; PG8_SCHED;
;             PG8_LDA(At, 0, 1); PG8_STAGE(PG8_SB(0, 0), b2, voffB); PG8_STAGE(PG8_SB(0, 1), b2 + hstep, voffB); PG8_STAGE(PG8_SA(0, 0), a2, voffA);
;             PG8_WAIT_V(8); PG8_WAIT_L(0); PG8_BAR; PG8_MMA(1, 0, At, B0); PG8_MMA(1, 1, At, B1); PG8_BAR; PG8_SCHED;
.LBB0_516:
	s_add_u32 s20, s18, 0x100
	s_addc_u32 s21, s19, 0
	s_cmp_lg_u32 s38, 4
	s_cselect_b32 s22, s20, 0
	s_cselect_b32 s23, s21, 0
	s_add_u32 s24, s16, s22
	s_addc_u32 s25, s17, s23
	s_add_i32 s39, 0, 0x10000
	s_add_u32 s22, s14, s22
	s_addc_u32 s23, s15, s23
	s_add_i32 s40, 0, 0x14000
	v_add_u32_e32 v156, s39, v142
	v_add_u32_e32 v172, s40, v142
	ds_read_b128 v[144:147], v156
	ds_read_b128 v[148:151], v156 offset:1024
	ds_read_b128 v[152:155], v156 offset:2048
	ds_read_b128 v[156:159], v156 offset:3072
	ds_read_b128 v[160:163], v172
	ds_read_b128 v[164:167], v172 offset:1024
	ds_read_b128 v[168:171], v172 offset:2048
	ds_read_b128 v[172:175], v172 offset:3072
	v_lshl_add_u64 v[192:193], v[138:139], 0, s[18:19]
	s_add_i32 m0, s1, 0xc000
	ds_read_b128 v[176:179], v143
	ds_read_b128 v[180:183], v143 offset:1024
	ds_read_b128 v[184:187], v143 offset:2048
	ds_read_b128 v[188:191], v143 offset:3072
	ds_read_b128 v[204:207], v143 offset:4096
	ds_read_b128 v[220:223], v143 offset:5120
	ds_read_b128 v[224:227], v143 offset:6144
	ds_read_b128 v[228:231], v143 offset:7168
	global_load_lds_dwordx4 v[192:193], off
	v_lshl_add_u64 v[192:193], v[140:141], 0, s[18:19]
	s_add_i32 m0, s1, 0xe000
	s_nop 0
	global_load_lds_dwordx4 v[192:193], off
	s_waitcnt vmcnt(8)
	s_waitcnt lgkmcnt(0)
	s_setprio 1
	s_barrier
	v_mfma_f32_16x16x32_bf16 v[58:61], v[144:147], v[176:179], v[58:61]
	v_mfma_f32_16x16x32_bf16 v[62:65], v[152:155], v[176:179], v[62:65]
	v_mfma_f32_16x16x32_bf16 v[42:45], v[144:147], v[184:187], v[42:45]
	v_mfma_f32_16x16x32_bf16 v[46:49], v[152:155], v[184:187], v[46:49]
	v_mfma_f32_16x16x32_bf16 v[26:29], v[144:147], v[204:207], v[26:29]
	v_mfma_f32_16x16x32_bf16 v[30:33], v[152:155], v[204:207], v[30:33]
	v_mfma_f32_16x16x32_bf16 v[10:13], v[144:147], v[224:227], v[10:13]
	v_mfma_f32_16x16x32_bf16 v[14:17], v[152:155], v[224:227], v[14:17]
	v_mfma_f32_16x16x32_bf16 v[58:61], v[148:151], v[180:183], v[58:61]
	v_mfma_f32_16x16x32_bf16 v[62:65], v[156:159], v[180:183], v[62:65]
	v_mfma_f32_16x16x32_bf16 v[42:45], v[148:151], v[188:191], v[42:45]
	v_mfma_f32_16x16x32_bf16 v[46:49], v[156:159], v[188:191], v[46:49]
	v_mfma_f32_16x16x32_bf16 v[26:29], v[148:151], v[220:223], v[26:29]
	v_mfma_f32_16x16x32_bf16 v[30:33], v[156:159], v[220:223], v[30:33]
	v_mfma_f32_16x16x32_bf16 v[10:13], v[148:151], v[228:231], v[10:13]
	v_mfma_f32_16x16x32_bf16 v[14:17], v[156:159], v[228:231], v[14:17]
	s_setprio 0
	s_setprio 1
	v_mfma_f32_16x16x32_bf16 v[50:53], v[160:163], v[176:179], v[50:53]
	v_mfma_f32_16x16x32_bf16 v[54:57], v[168:171], v[176:179], v[54:57]
	v_mfma_f32_16x16x32_bf16 v[34:37], v[160:163], v[184:187], v[34:37]
	v_mfma_f32_16x16x32_bf16 v[38:41], v[168:171], v[184:187], v[38:41]
	v_mfma_f32_16x16x32_bf16 v[18:21], v[160:163], v[204:207], v[18:21]
	v_mfma_f32_16x16x32_bf16 v[22:25], v[168:171], v[204:207], v[22:25]
	v_mfma_f32_16x16x32_bf16 v[2:5], v[160:163], v[224:227], v[2:5]
	v_mfma_f32_16x16x32_bf16 v[6:9], v[168:171], v[224:227], v[6:9]
	v_mfma_f32_16x16x32_bf16 v[50:53], v[164:167], v[180:183], v[50:53]
	v_mfma_f32_16x16x32_bf16 v[54:57], v[172:175], v[180:183], v[54:57]
	v_mfma_f32_16x16x32_bf16 v[34:37], v[164:167], v[188:191], v[34:37]
	v_mfma_f32_16x16x32_bf16 v[38:41], v[172:175], v[188:191], v[38:41]
	v_mfma_f32_16x16x32_bf16 v[18:21], v[164:167], v[220:223], v[18:21]
	v_mfma_f32_16x16x32_bf16 v[22:25], v[172:175], v[220:223], v[22:25]
	v_mfma_f32_16x16x32_bf16 v[2:5], v[164:167], v[228:231], v[2:5]
	v_mfma_f32_16x16x32_bf16 v[6:9], v[172:175], v[228:231], v[6:9]
	s_barrier
	s_setprio 0
	s_add_i32 s18, s39, s3
	v_lshl_add_u64 v[192:193], s[22:23], 0, v[0:1]
	s_mov_b32 m0, s18
	ds_read_b128 v[176:179], v143 offset:16384
	ds_read_b128 v[180:183], v143 offset:17408
	ds_read_b128 v[184:187], v143 offset:18432
	ds_read_b128 v[188:191], v143 offset:19456
	ds_read_b128 v[204:207], v143 offset:20480
	ds_read_b128 v[220:223], v143 offset:21504
	ds_read_b128 v[224:227], v143 offset:22528
	ds_read_b128 v[228:231], v143 offset:23552
	global_load_lds_dwordx4 v[192:193], off
	s_add_i32 m0, s18, 0x2000
	s_add_u32 s18, s22, 0x80000
	v_lshl_add_u64 v[200:201], s[22:23], 0, v[136:137]
	s_addc_u32 s19, s23, 0
	s_add_i32 s39, s40, s3
	global_load_lds_dwordx4 v[200:201], off
	s_nop 0
	s_mov_b32 m0, s39
	v_lshl_add_u64 v[232:233], s[24:25], 0, v[134:135]
	global_load_lds_dwordx4 v0, s[18:19]
	s_nop 0
	s_add_i32 m0, s39, 0x2000
	s_nop 0
	global_load_lds_dwordx4 v136, s[18:19]
	v_lshl_add_u64 v[202:203], s[24:25], 0, v[132:133]
	s_mov_b32 m0, s1
	s_nop 0
	global_load_lds_dwordx4 v[202:203], off
	s_mov_b32 m0, s10
	s_nop 0
	global_load_lds_dwordx4 v[232:233], off
	s_waitcnt vmcnt(8)
	s_waitcnt lgkmcnt(0)
	s_setprio 1
	s_barrier
; #define PG8_STAGE(bufoff, gbase, voff) do { _Pragma("unroll") for (int _i = 0; _i < 2; ++_i) \
;         __builtin_amdgcn_global_load_lds((const unsigned*)((const char*)(gbase) + (voff)[_i]), (PG8_LAS unsigned*)(lds + (bufoff) + ldsw + _i * 8192), 16, 0, 0); } while (0)
; #define PG8_LDA(dst, b, h) do { _Pragma("unroll") for (int m = 0; m < 4; ++m) _Pragma("unroll") for (int k = 0; k < 2; ++k) dst[m][k] = *(const PG8_LAS bf16x8*)(lds + PG8_SA(b, h) + aoff + m * 2048 + k * 1024); } while (0)
; #define PG8_LDB(dst, b, h) do { _Pragma("unroll") for (int n = 0; n < 2; ++n) _Pragma("unroll") for (int k = 0; k < 2; ++k) dst[n][k] = *(const PG8_LAS bf16x8*)(lds + PG8_SB(b, h) + boff + n * 2048 + k * 1024); } while (0)
; #define PG8_MMA(ai, bj, At, Bt) do { __builtin_amdgcn_s_setprio(1); _Pragma("unroll") for (int m = 0; m < 4; ++m) _Pragma("unroll") for (int n = 0; n < 2; ++n) _Pragma("unroll") for (int k = 0; k < 2; ++k) \
;         acc[ai][bj][m][n] = __builtin_amdgcn_mfma_f32_16x16x32_bf16(Bt[n][k], At[m][k], acc[ai][bj][m][n], 0, 0, 0); __builtin_amdgcn_s_setprio(0); } while (0)
; #define PG8_WAIT_V(n) asm volatile("s_waitcnt vmcnt(" #n ")" ::: "memory")
; #define PG8_WAIT_L(n) asm volatile("s_waitcnt lgkmcnt(" #n ")" ::: "memory")
; #define PG8_BAR __builtin_amdgcn_s_barrier()
; #define PG8_SCHED __builtin_amdgcn_sched_barrier(0)
; template <class Epi, class Sched, bool ALIGN_EPI = false, bool SP2 = false>
; __device__ __forceinline__ void gemm_phase(PG8_LAS unsigned char* lds, const Gemm g, const Sched& S, const Epi& E) {
;     ...
;             PG8_WAIT_V(8); PG8_WAIT_L(0); PG8_BAR; PG8_MMA(1, 0, At, B0); PG8_MMA(1, 1, At, B1); PG8_BAR; PG8_SCHED;
;             PG8_LDB(B0, 1, 0); PG8_LDB(B1, 1, 1); PG8_SCHED; PG8_LDA(At, 1, 0); PG8_STAGE(PG8_SA(0, 1), a2 + hstep, voffA);
;             PG8_WAIT_V(8); PG8_WAIT_L(0); PG8_BAR; PG8_MMA(0, 0, At, B0); PG8_MMA(0, 1, At, B1); PG8_BAR; PG8_SCHED;
;             PG8_LDA(At, 1, 1); PG8_STAGE(PG8_SB(1, 0), b3, voffB); PG8_STAGE(PG8_SB(1, 1), b3 + hstep, voffB); PG8_STAGE(PG8_SA(1, 0), a3, voffA);
	v_mfma_f32_16x16x32_bf16 v[90:93], v[144:147], v[176:179], v[90:93]
	v_mfma_f32_16x16x32_bf16 v[94:97], v[152:155], v[176:179], v[94:97]
	v_mfma_f32_16x16x32_bf16 v[74:77], v[144:147], v[184:187], v[74:77]
	v_mfma_f32_16x16x32_bf16 v[78:81], v[152:155], v[184:187], v[78:81]
	v_mfma_f32_16x16x32_bf16 v[122:125], v[144:147], v[204:207], v[122:125]
	v_mfma_f32_16x16x32_bf16 v[126:129], v[152:155], v[204:207], v[126:129]
	v_mfma_f32_16x16x32_bf16 v[106:109], v[144:147], v[224:227], v[106:109]
	v_mfma_f32_16x16x32_bf16 v[110:113], v[152:155], v[224:227], v[110:113]
	v_mfma_f32_16x16x32_bf16 v[90:93], v[148:151], v[180:183], v[90:93]
	v_mfma_f32_16x16x32_bf16 v[94:97], v[156:159], v[180:183], v[94:97]
	v_mfma_f32_16x16x32_bf16 v[74:77], v[148:151], v[188:191], v[74:77]
	v_mfma_f32_16x16x32_bf16 v[78:81], v[156:159], v[188:191], v[78:81]
	v_mfma_f32_16x16x32_bf16 v[122:125], v[148:151], v[220:223], v[122:125]
	v_mfma_f32_16x16x32_bf16 v[126:129], v[156:159], v[220:223], v[126:129]
	v_mfma_f32_16x16x32_bf16 v[106:109], v[148:151], v[228:231], v[106:109]
	v_mfma_f32_16x16x32_bf16 v[110:113], v[156:159], v[228:231], v[110:113]
	s_setprio 0
	s_setprio 1
	v_mfma_f32_16x16x32_bf16 v[82:85], v[160:163], v[176:179], v[82:85]
	v_mfma_f32_16x16x32_bf16 v[86:89], v[168:171], v[176:179], v[86:89]
	v_mfma_f32_16x16x32_bf16 v[66:69], v[160:163], v[184:187], v[66:69]
	v_mfma_f32_16x16x32_bf16 v[70:73], v[168:171], v[184:187], v[70:73]
	v_mfma_f32_16x16x32_bf16 v[114:117], v[160:163], v[204:207], v[114:117]
	v_mfma_f32_16x16x32_bf16 v[118:121], v[168:171], v[204:207], v[118:121]
	v_mfma_f32_16x16x32_bf16 v[102:105], v[160:163], v[224:227], v[102:105]
	v_mfma_f32_16x16x32_bf16 v[98:101], v[168:171], v[224:227], v[98:101]
	v_mfma_f32_16x16x32_bf16 v[82:85], v[164:167], v[180:183], v[82:85]
	v_mfma_f32_16x16x32_bf16 v[86:89], v[172:175], v[180:183], v[86:89]
	v_mfma_f32_16x16x32_bf16 v[66:69], v[164:167], v[188:191], v[66:69]
	v_mfma_f32_16x16x32_bf16 v[70:73], v[172:175], v[188:191], v[70:73]
	v_mfma_f32_16x16x32_bf16 v[114:117], v[164:167], v[220:223], v[114:117]
	v_mfma_f32_16x16x32_bf16 v[118:121], v[172:175], v[220:223], v[118:121]
	v_mfma_f32_16x16x32_bf16 v[102:105], v[164:167], v[228:231], v[102:105]
	v_mfma_f32_16x16x32_bf16 v[98:101], v[172:175], v[228:231], v[98:101]
	s_barrier
	s_setprio 0
	s_add_i32 s39, 0, 0x18000
	s_add_i32 s40, 0, 0x1c000
	v_add_u32_e32 v156, s39, v142
	v_add_u32_e32 v172, s40, v142
	ds_read_b128 v[144:147], v156
	ds_read_b128 v[148:151], v156 offset:1024
	ds_read_b128 v[152:155], v156 offset:2048
	ds_read_b128 v[156:159], v156 offset:3072
	ds_read_b128 v[160:163], v172
	ds_read_b128 v[164:167], v172 offset:1024
	ds_read_b128 v[168:171], v172 offset:2048
	ds_read_b128 v[172:175], v172 offset:3072
	s_add_u32 s18, s24, 0x80000
	s_addc_u32 s19, s25, 0
	s_mov_b32 m0, s11
	v_lshl_add_u64 v[234:235], s[18:19], 0, v[132:133]
	ds_read_b128 v[176:179], v143 offset:32768
	ds_read_b128 v[180:183], v143 offset:33792
	ds_read_b128 v[184:187], v143 offset:34816
	ds_read_b128 v[188:191], v143 offset:35840
	ds_read_b128 v[204:207], v143 offset:36864
	ds_read_b128 v[220:223], v143 offset:37888
	ds_read_b128 v[224:227], v143 offset:38912
	ds_read_b128 v[228:231], v143 offset:39936
	global_load_lds_dwordx4 v[234:235], off
	v_lshl_add_u64 v[234:235], s[18:19], 0, v[134:135]
	s_mov_b32 m0, s27
	s_nop 0
	global_load_lds_dwordx4 v[234:235], off
	s_waitcnt vmcnt(8)
	s_waitcnt lgkmcnt(0)
	s_setprio 1
	s_barrier
	v_mfma_f32_16x16x32_bf16 v[58:61], v[144:147], v[176:179], v[58:61]
	v_mfma_f32_16x16x32_bf16 v[62:65], v[152:155], v[176:179], v[62:65]
	v_mfma_f32_16x16x32_bf16 v[42:45], v[144:147], v[184:187], v[42:45]
	v_mfma_f32_16x16x32_bf16 v[46:49], v[152:155], v[184:187], v[46:49]
	v_mfma_f32_16x16x32_bf16 v[26:29], v[144:147], v[204:207], v[26:29]
	v_mfma_f32_16x16x32_bf16 v[30:33], v[152:155], v[204:207], v[30:33]
	v_mfma_f32_16x16x32_bf16 v[10:13], v[144:147], v[224:227], v[10:13]
	v_mfma_f32_16x16x32_bf16 v[14:17], v[152:155], v[224:227], v[14:17]
	v_mfma_f32_16x16x32_bf16 v[58:61], v[148:151], v[180:183], v[58:61]
	v_mfma_f32_16x16x32_bf16 v[62:65], v[156:159], v[180:183], v[62:65]
	v_mfma_f32_16x16x32_bf16 v[42:45], v[148:151], v[188:191], v[42:45]
	v_mfma_f32_16x16x32_bf16 v[46:49], v[156:159], v[188:191], v[46:49]
	v_mfma_f32_16x16x32_bf16 v[26:29], v[148:151], v[220:223], v[26:29]
	v_mfma_f32_16x16x32_bf16 v[30:33], v[156:159], v[220:223], v[30:33]
	v_mfma_f32_16x16x32_bf16 v[10:13], v[148:151], v[228:231], v[10:13]
	v_mfma_f32_16x16x32_bf16 v[14:17], v[156:159], v[228:231], v[14:17]
	s_setprio 0
	s_setprio 1
	v_mfma_f32_16x16x32_bf16 v[50:53], v[160:163], v[176:179], v[50:53]
	v_mfma_f32_16x16x32_bf16 v[54:57], v[168:171], v[176:179], v[54:57]
	v_mfma_f32_16x16x32_bf16 v[34:37], v[160:163], v[184:187], v[34:37]
	v_mfma_f32_16x16x32_bf16 v[38:41], v[168:171], v[184:187], v[38:41]
	v_mfma_f32_16x16x32_bf16 v[18:21], v[160:163], v[204:207], v[18:21]
	v_mfma_f32_16x16x32_bf16 v[22:25], v[168:171], v[204:207], v[22:25]
	v_mfma_f32_16x16x32_bf16 v[2:5], v[160:163], v[224:227], v[2:5]
	v_mfma_f32_16x16x32_bf16 v[6:9], v[168:171], v[224:227], v[6:9]
	v_mfma_f32_16x16x32_bf16 v[50:53], v[164:167], v[180:183], v[50:53]
	v_mfma_f32_16x16x32_bf16 v[54:57], v[172:175], v[180:183], v[54:57]
	v_mfma_f32_16x16x32_bf16 v[34:37], v[164:167], v[188:191], v[34:37]
	v_mfma_f32_16x16x32_bf16 v[38:41], v[172:175], v[188:191], v[38:41]
	v_mfma_f32_16x16x32_bf16 v[18:21], v[164:167], v[220:223], v[18:21]
	v_mfma_f32_16x16x32_bf16 v[22:25], v[172:175], v[220:223], v[22:25]
	v_mfma_f32_16x16x32_bf16 v[2:5], v[164:167], v[228:231], v[2:5]
	v_mfma_f32_16x16x32_bf16 v[6:9], v[172:175], v[228:231], v[6:9]
	s_barrier
; #define PG8_STAGE(bufoff, gbase, voff) do { _Pragma("unroll") for (int _i = 0; _i < 2; ++_i) \
;         __builtin_amdgcn_global_load_lds((const unsigned*)((const char*)(gbase) + (voff)[_i]), (PG8_LAS unsigned*)(lds + (bufoff) + ldsw + _i * 8192), 16, 0, 0); } while (0)
; #define PG8_LDA(dst, b, h) do { _Pragma("unroll") for (int m = 0; m < 4; ++m) _Pragma("unroll") for (int k = 0; k < 2; ++k) dst[m][k] = *(const PG8_LAS bf16x8*)(lds + PG8_SA(b, h) + aoff + m * 2048 + k * 1024); } while (0)
; #define PG8_MMA(ai, bj, At, Bt) do { __builtin_amdgcn_s_setprio(1); _Pragma("unroll") for (int m = 0; m < 4; ++m) _Pragma("unroll") for (int n = 0; n < 2; ++n) _Pragma("unroll") for (int k = 0; k < 2; ++k) \
;         acc[ai][bj][m][n] = __builtin_amdgcn_mfma_f32_16x16x32_bf16(Bt[n][k], At[m][k], acc[ai][bj][m][n], 0, 0, 0); __builtin_amdgcn_s_setprio(0); } while (0)
; #define PG8_WAIT_V(n) asm volatile("s_waitcnt vmcnt(" #n ")" ::: "memory")
; #define PG8_WAIT_L(n) asm volatile("s_waitcnt lgkmcnt(" #n ")" ::: "memory")
; #define PG8_BAR __builtin_amdgcn_s_barrier()
; #define PG8_SCHED __builtin_amdgcn_sched_barrier(0)
; template <class Epi, class Sched, bool ALIGN_EPI = false, bool SP2 = false>
; __device__ __forceinline__ void gemm_phase(PG8_LAS unsigned char* lds, const Gemm g, const Sched& S, const Epi& E) {
;     ...
;             PG8_LDA(At, 1, 1); PG8_STAGE(PG8_SB(1, 0), b3, voffB); PG8_STAGE(PG8_SB(1, 1), b3 + hstep, voffB); PG8_STAGE(PG8_SA(1, 0), a3, voffA);
;             PG8_WAIT_V(8); PG8_WAIT_L(0); PG8_BAR; PG8_MMA(1, 0, At, B0); PG8_MMA(1, 1, At, B1); PG8_BAR; PG8_SCHED;
;     ...
;         if constexpr (ALIGN_EPI) { if (wr == 0) PG8_BAR; }
	s_setprio 0
	s_add_i32 s18, s39, s3
	v_lshl_add_u64 v[192:193], v[192:193], 0, s[56:57]
	s_mov_b32 m0, s18
	ds_read_b128 v[176:179], v143 offset:49152
	ds_read_b128 v[180:183], v143 offset:50176
	ds_read_b128 v[184:187], v143 offset:51200
	ds_read_b128 v[188:191], v143 offset:52224
	ds_read_b128 v[204:207], v143 offset:53248
	ds_read_b128 v[220:223], v143 offset:54272
	ds_read_b128 v[224:227], v143 offset:55296
	ds_read_b128 v[228:231], v143 offset:56320
	global_load_lds_dwordx4 v[192:193], off
	s_add_i32 m0, s18, 0x2000
	s_add_u32 s18, s22, 0x80080
	v_lshl_add_u64 v[192:193], v[200:201], 0, s[56:57]
	s_addc_u32 s19, s23, 0
	s_add_i32 s22, s40, s3
	global_load_lds_dwordx4 v[192:193], off
	s_nop 0
	s_mov_b32 m0, s22
	s_nop 0
	global_load_lds_dwordx4 v0, s[18:19]
	s_nop 0
	s_add_i32 m0, s22, 0x2000
	s_nop 0
	global_load_lds_dwordx4 v136, s[18:19]
	v_lshl_add_u64 v[192:193], v[202:203], 0, s[56:57]
	s_mov_b32 m0, s33
	s_nop 0
	global_load_lds_dwordx4 v[192:193], off
	v_lshl_add_u64 v[192:193], v[232:233], 0, s[56:57]
	s_mov_b32 m0, s37
	s_nop 0
	global_load_lds_dwordx4 v[192:193], off
	s_waitcnt vmcnt(8)
	s_waitcnt lgkmcnt(0)
	s_setprio 1
	s_barrier
	v_mfma_f32_16x16x32_bf16 v[90:93], v[144:147], v[176:179], v[90:93]
	v_mfma_f32_16x16x32_bf16 v[94:97], v[152:155], v[176:179], v[94:97]
	v_mfma_f32_16x16x32_bf16 v[74:77], v[144:147], v[184:187], v[74:77]
	v_mfma_f32_16x16x32_bf16 v[78:81], v[152:155], v[184:187], v[78:81]
	v_mfma_f32_16x16x32_bf16 v[122:125], v[144:147], v[204:207], v[122:125]
	v_mfma_f32_16x16x32_bf16 v[126:129], v[152:155], v[204:207], v[126:129]
	v_mfma_f32_16x16x32_bf16 v[106:109], v[144:147], v[224:227], v[106:109]
	v_mfma_f32_16x16x32_bf16 v[110:113], v[152:155], v[224:227], v[110:113]
	v_mfma_f32_16x16x32_bf16 v[90:93], v[148:151], v[180:183], v[90:93]
	v_mfma_f32_16x16x32_bf16 v[94:97], v[156:159], v[180:183], v[94:97]
	v_mfma_f32_16x16x32_bf16 v[74:77], v[148:151], v[188:191], v[74:77]
	v_mfma_f32_16x16x32_bf16 v[78:81], v[156:159], v[188:191], v[78:81]
	v_mfma_f32_16x16x32_bf16 v[122:125], v[148:151], v[220:223], v[122:125]
	v_mfma_f32_16x16x32_bf16 v[126:129], v[156:159], v[220:223], v[126:129]
	v_mfma_f32_16x16x32_bf16 v[106:109], v[148:151], v[228:231], v[106:109]
	v_mfma_f32_16x16x32_bf16 v[110:113], v[156:159], v[228:231], v[110:113]
	s_setprio 0
	s_setprio 1
	v_mfma_f32_16x16x32_bf16 v[82:85], v[160:163], v[176:179], v[82:85]
	v_mfma_f32_16x16x32_bf16 v[86:89], v[168:171], v[176:179], v[86:89]
	v_mfma_f32_16x16x32_bf16 v[66:69], v[160:163], v[184:187], v[66:69]
	v_mfma_f32_16x16x32_bf16 v[70:73], v[168:171], v[184:187], v[70:73]
	v_mfma_f32_16x16x32_bf16 v[114:117], v[160:163], v[204:207], v[114:117]
	v_mfma_f32_16x16x32_bf16 v[118:121], v[168:171], v[204:207], v[118:121]
	v_mfma_f32_16x16x32_bf16 v[102:105], v[160:163], v[224:227], v[102:105]
	v_mfma_f32_16x16x32_bf16 v[98:101], v[168:171], v[224:227], v[98:101]
	v_mfma_f32_16x16x32_bf16 v[82:85], v[164:167], v[180:183], v[82:85]
	v_mfma_f32_16x16x32_bf16 v[86:89], v[172:175], v[180:183], v[86:89]
	v_mfma_f32_16x16x32_bf16 v[66:69], v[164:167], v[188:191], v[66:69]
	v_mfma_f32_16x16x32_bf16 v[70:73], v[172:175], v[188:191], v[70:73]
	v_mfma_f32_16x16x32_bf16 v[114:117], v[164:167], v[220:223], v[114:117]
	v_mfma_f32_16x16x32_bf16 v[118:121], v[172:175], v[220:223], v[118:121]
	v_mfma_f32_16x16x32_bf16 v[102:105], v[164:167], v[228:231], v[102:105]
	v_mfma_f32_16x16x32_bf16 v[98:101], v[172:175], v[228:231], v[98:101]
	s_barrier
	s_setprio 0
	s_add_i32 s38, s38, 2
	s_cmp_gt_u32 s38, 5
	s_mov_b64 s[18:19], s[20:21]
	s_cbranch_scc0 .LBB0_516
	s_cmpk_lt_u32 s2, 0x100
	s_cbranch_scc0 .LBB0_519
	s_barrier

; #define PG8_STAGE(bufoff, gbase, voff) do { _Pragma("unroll") for (int _i = 0; _i < 2; ++_i) \
;         __builtin_amdgcn_global_load_lds((const unsigned*)((const char*)(gbase) + (voff)[_i]), (PG8_LAS unsigned*)(lds + (bufoff) + ldsw + _i * 8192), 16, 0, 0); } while (0)
; #define PG8_LDA(dst, b, h) do { _Pragma("unroll") for (int m = 0; m < 4; ++m) _Pragma("unroll") for (int k = 0; k < 2; ++k) dst[m][k] = *(const PG8_LAS bf16x8*)(lds + PG8_SA(b, h) + aoff + m * 2048 + k * 1024); } while (0)
; #define PG8_LDB(dst, b, h) do { _Pragma("unroll") for (int n = 0; n < 2; ++n) _Pragma("unroll") for (int k = 0; k < 2; ++k) dst[n][k] = *(const PG8_LAS bf16x8*)(lds + PG8_SB(b, h) + boff + n * 2048 + k * 1024); } while (0)
; #define PG8_MMA(ai, bj, At, Bt) do { __builtin_amdgcn_s_setprio(1); _Pragma("unroll") for (int m = 0; m < 4; ++m) _Pragma("unroll") for (int n = 0; n < 2; ++n) _Pragma("unroll") for (int k = 0; k < 2; ++k) \
;         acc[ai][bj][m][n] = __builtin_amdgcn_mfma_f32_16x16x32_bf16(Bt[n][k], At[m][k], acc[ai][bj][m][n], 0, 0, 0); __builtin_amdgcn_s_setprio(0); } while (0)
; #define PG8_WAIT_V(n) asm volatile("s_waitcnt vmcnt(" #n ")" ::: "memory")
; #define PG8_BAR __builtin_amdgcn_s_barrier()
; template <class Epi, class Sched, bool ALIGN_EPI = false, bool SP2 = false>
; __device__ __forceinline__ void gemm_phase(PG8_LAS unsigned char* lds, const Gemm g, const Sched& S, const Epi& E) {
;     ...
;         for (int t = 0; t < nt; t += 2) {
;             const bool last = (t == nt - 2);
;             const char* a1 = cA + (size_t)(t + 1) * kstep;
;             const char* a2 = last ? nA : cA + (size_t)(t + 2) * kstep; const char* b2 = last ? nB : cB + (size_t)(t + 2) * kstep;
;             const char* a3 = a2 + kstep; const char* b3 = b2 + kstep;
;             if (last && has_next) S.a_ready(nxt);
;             if constexpr (SP2) {
;             PG8_LDB(B0, 0, 0); PG8_LDB(B1, 0, 1); PG8_SCHED; PG8_LDA(At, 0, 0); PG8_STAGE(PG8_SA(1, 1), a1 + hstep, voffA);
;             PG8_WAIT_V(8); PG8_WAIT_L(0); PG8_BAR; PG8_MMA(0, 0, At, B0); PG8_MMA(0, 1, At, B1); PG8_BAR; PG8_SCHED;
;             PG8_LDA(At, 0, 1); PG8_STAGE(PG8_SB(0, 0), b2, voffB); PG8_STAGE(PG8_SB(0, 1), b2 + hstep, voffB); PG8_STAGE(PG8_SA(0, 0), a2, voffA);
;             PG8_WAIT_V(8); PG8_WAIT_L(0); PG8_BAR; PG8_MMA(1, 0, At, B0); PG8_MMA(1, 1, At, B1); PG8_BAR; PG8_SCHED;
.LBB0_643:
	s_add_u32 s44, s24, 0xfff80080
	s_addc_u32 s45, s25, -1
	s_add_i32 s74, 0, 0x10000
	s_cmp_eq_u32 s51, 28
	s_cselect_b32 s49, s21, s45
	s_cselect_b32 s48, s20, s44
	v_add_u32_e32 v0, s74, v192
	s_cselect_b32 s45, s19, s47
	s_cselect_b32 s44, s26, s27
	s_add_i32 s73, 0, 0x14000
	ds_read_b128 v[130:133], v0
	ds_read_b128 v[134:137], v0 offset:1024
	ds_read_b128 v[138:141], v0 offset:2048
	ds_read_b128 v[142:145], v0 offset:3072
	v_add_u32_e32 v0, s73, v192
	ds_read_b128 v[146:149], v0
	ds_read_b128 v[150:153], v0 offset:1024
	ds_read_b128 v[168:171], v0 offset:2048
	ds_read_b128 v[172:175], v0 offset:3072
	v_lshl_add_u64 v[154:155], s[24:25], 0, v[164:165]
	s_add_i32 m0, s77, 0xc000
	ds_read_b128 v[176:179], v193
	ds_read_b128 v[180:183], v193 offset:1024
	ds_read_b128 v[186:189], v193 offset:2048
	ds_read_b128 v[204:207], v193 offset:3072
	ds_read_b128 v[218:221], v193 offset:4096
	ds_read_b128 v[222:225], v193 offset:5120
	ds_read_b128 v[226:229], v193 offset:6144
	ds_read_b128 v[230:233], v193 offset:7168
	global_load_lds_dwordx4 v[154:155], off
	s_nop 0
	s_add_i32 m0, s77, 0xe000
	s_nop 0
	global_load_lds_dwordx4 v166, s[24:25]
	s_waitcnt vmcnt(8)
	s_waitcnt lgkmcnt(0)
	s_setprio 1
	s_barrier
	v_mfma_f32_16x16x32_bf16 v[126:129], v[130:133], v[176:179], v[126:129]
	v_mfma_f32_16x16x32_bf16 v[122:125], v[138:141], v[176:179], v[122:125]
	v_mfma_f32_16x16x32_bf16 v[110:113], v[130:133], v[186:189], v[110:113]
	v_mfma_f32_16x16x32_bf16 v[106:109], v[138:141], v[186:189], v[106:109]
	v_mfma_f32_16x16x32_bf16 v[94:97], v[130:133], v[218:221], v[94:97]
	v_mfma_f32_16x16x32_bf16 v[90:93], v[138:141], v[218:221], v[90:93]
	v_mfma_f32_16x16x32_bf16 v[78:81], v[130:133], v[226:229], v[78:81]
	v_mfma_f32_16x16x32_bf16 v[74:77], v[138:141], v[226:229], v[74:77]
	v_mfma_f32_16x16x32_bf16 v[126:129], v[134:137], v[180:183], v[126:129]
	v_mfma_f32_16x16x32_bf16 v[122:125], v[142:145], v[180:183], v[122:125]
	v_mfma_f32_16x16x32_bf16 v[110:113], v[134:137], v[204:207], v[110:113]
	v_mfma_f32_16x16x32_bf16 v[106:109], v[142:145], v[204:207], v[106:109]
	v_mfma_f32_16x16x32_bf16 v[94:97], v[134:137], v[222:225], v[94:97]
	v_mfma_f32_16x16x32_bf16 v[90:93], v[142:145], v[222:225], v[90:93]
	v_mfma_f32_16x16x32_bf16 v[78:81], v[134:137], v[230:233], v[78:81]
	v_mfma_f32_16x16x32_bf16 v[74:77], v[142:145], v[230:233], v[74:77]
	s_setprio 0
	s_setprio 1
	v_mfma_f32_16x16x32_bf16 v[114:117], v[146:149], v[176:179], v[114:117]
	v_mfma_f32_16x16x32_bf16 v[118:121], v[168:171], v[176:179], v[118:121]
	v_mfma_f32_16x16x32_bf16 v[98:101], v[146:149], v[186:189], v[98:101]
	v_mfma_f32_16x16x32_bf16 v[102:105], v[168:171], v[186:189], v[102:105]
	v_mfma_f32_16x16x32_bf16 v[82:85], v[146:149], v[218:221], v[82:85]
	v_mfma_f32_16x16x32_bf16 v[86:89], v[168:171], v[218:221], v[86:89]
	v_mfma_f32_16x16x32_bf16 v[66:69], v[146:149], v[226:229], v[66:69]
	v_mfma_f32_16x16x32_bf16 v[70:73], v[168:171], v[226:229], v[70:73]
	v_mfma_f32_16x16x32_bf16 v[114:117], v[150:153], v[180:183], v[114:117]
	v_mfma_f32_16x16x32_bf16 v[118:121], v[172:175], v[180:183], v[118:121]
	v_mfma_f32_16x16x32_bf16 v[98:101], v[150:153], v[204:207], v[98:101]
	v_mfma_f32_16x16x32_bf16 v[102:105], v[172:175], v[204:207], v[102:105]
	v_mfma_f32_16x16x32_bf16 v[82:85], v[150:153], v[222:225], v[82:85]
	v_mfma_f32_16x16x32_bf16 v[86:89], v[172:175], v[222:225], v[86:89]
	v_mfma_f32_16x16x32_bf16 v[66:69], v[150:153], v[230:233], v[66:69]
	v_mfma_f32_16x16x32_bf16 v[70:73], v[172:175], v[230:233], v[70:73]
	s_barrier
	s_setprio 0
	s_add_i32 s74, s74, s76
	v_lshl_add_u64 v[154:155], s[44:45], 0, v[158:159]
	s_mov_b32 m0, s74
	ds_read_b128 v[176:179], v193 offset:16384
	ds_read_b128 v[180:183], v193 offset:17408
	ds_read_b128 v[186:189], v193 offset:18432
	ds_read_b128 v[204:207], v193 offset:19456
	ds_read_b128 v[218:221], v193 offset:20480
	ds_read_b128 v[222:225], v193 offset:21504
	ds_read_b128 v[226:229], v193 offset:22528
	ds_read_b128 v[230:233], v193 offset:23552
	global_load_lds_dwordx4 v[154:155], off
	s_add_i32 m0, s74, 0x2000
	s_add_u32 vcc_lo, s44, 0x80000
	v_lshl_add_u64 v[200:201], s[44:45], 0, v[162:163]
	s_addc_u32 vcc_hi, s45, 0
	s_add_i32 s73, s73, s76
	global_load_lds_dwordx4 v[200:201], off
	v_lshl_add_u64 v[202:203], vcc, 0, v[158:159]
	s_mov_b32 m0, s73
	v_lshl_add_u64 v[234:235], s[48:49], 0, v[160:161]
	global_load_lds_dwordx4 v[202:203], off
	v_lshl_add_u64 v[202:203], vcc, 0, v[162:163]
	s_add_i32 m0, s73, 0x2000
	s_nop 0
	global_load_lds_dwordx4 v[202:203], off
	v_lshl_add_u64 v[202:203], s[48:49], 0, v[156:157]
	s_mov_b32 m0, s77
	s_nop 0
	global_load_lds_dwordx4 v[202:203], off
	s_mov_b32 m0, s78
	s_nop 0
	global_load_lds_dwordx4 v[234:235], off
	s_waitcnt vmcnt(8)
	s_waitcnt lgkmcnt(0)
	s_setprio 1
	s_barrier
; #define PG8_STAGE(bufoff, gbase, voff) do { _Pragma("unroll") for (int _i = 0; _i < 2; ++_i) \
;         __builtin_amdgcn_global_load_lds((const unsigned*)((const char*)(gbase) + (voff)[_i]), (PG8_LAS unsigned*)(lds + (bufoff) + ldsw + _i * 8192), 16, 0, 0); } while (0)
; #define PG8_LDA(dst, b, h) do { _Pragma("unroll") for (int m = 0; m < 4; ++m) _Pragma("unroll") for (int k = 0; k < 2; ++k) dst[m][k] = *(const PG8_LAS bf16x8*)(lds + PG8_SA(b, h) + aoff + m * 2048 + k * 1024); } while (0)
; #define PG8_LDB(dst, b, h) do { _Pragma("unroll") for (int n = 0; n < 2; ++n) _Pragma("unroll") for (int k = 0; k < 2; ++k) dst[n][k] = *(const PG8_LAS bf16x8*)(lds + PG8_SB(b, h) + boff + n * 2048 + k * 1024); } while (0)
; #define PG8_MMA(ai, bj, At, Bt) do { __builtin_amdgcn_s_setprio(1); _Pragma("unroll") for (int m = 0; m < 4; ++m) _Pragma("unroll") for (int n = 0; n < 2; ++n) _Pragma("unroll") for (int k = 0; k < 2; ++k) \
;         acc[ai][bj][m][n] = __builtin_amdgcn_mfma_f32_16x16x32_bf16(Bt[n][k], At[m][k], acc[ai][bj][m][n], 0, 0, 0); __builtin_amdgcn_s_setprio(0); } while (0)
; #define PG8_WAIT_V(n) asm volatile("s_waitcnt vmcnt(" #n ")" ::: "memory")
; #define PG8_WAIT_L(n) asm volatile("s_waitcnt lgkmcnt(" #n ")" ::: "memory")
; #define PG8_BAR __builtin_amdgcn_s_barrier()
; #define PG8_SCHED __builtin_amdgcn_sched_barrier(0)
; template <class Epi, class Sched, bool ALIGN_EPI = false, bool SP2 = false>
; __device__ __forceinline__ void gemm_phase(PG8_LAS unsigned char* lds, const Gemm g, const Sched& S, const Epi& E) {
;     ...
;             PG8_WAIT_V(8); PG8_WAIT_L(0); PG8_BAR; PG8_MMA(1, 0, At, B0); PG8_MMA(1, 1, At, B1); PG8_BAR; PG8_SCHED;
;             PG8_LDB(B0, 1, 0); PG8_LDB(B1, 1, 1); PG8_SCHED; PG8_LDA(At, 1, 0); PG8_STAGE(PG8_SA(0, 1), a2 + hstep, voffA);
;             PG8_WAIT_V(8); PG8_WAIT_L(0); PG8_BAR; PG8_MMA(0, 0, At, B0); PG8_MMA(0, 1, At, B1); PG8_BAR; PG8_SCHED;
;             PG8_LDA(At, 1, 1); PG8_STAGE(PG8_SB(1, 0), b3, voffB); PG8_STAGE(PG8_SB(1, 1), b3 + hstep, voffB); PG8_STAGE(PG8_SA(1, 0), a3, voffA);
	v_mfma_f32_16x16x32_bf16 v[62:65], v[130:133], v[176:179], v[62:65]
	v_mfma_f32_16x16x32_bf16 v[58:61], v[138:141], v[176:179], v[58:61]
	v_mfma_f32_16x16x32_bf16 v[46:49], v[130:133], v[186:189], v[46:49]
	v_mfma_f32_16x16x32_bf16 v[42:45], v[138:141], v[186:189], v[42:45]
	v_mfma_f32_16x16x32_bf16 v[30:33], v[130:133], v[218:221], v[30:33]
	v_mfma_f32_16x16x32_bf16 v[26:29], v[138:141], v[218:221], v[26:29]
	v_mfma_f32_16x16x32_bf16 v[14:17], v[130:133], v[226:229], v[14:17]
	v_mfma_f32_16x16x32_bf16 v[10:13], v[138:141], v[226:229], v[10:13]
	v_mfma_f32_16x16x32_bf16 v[62:65], v[134:137], v[180:183], v[62:65]
	v_mfma_f32_16x16x32_bf16 v[58:61], v[142:145], v[180:183], v[58:61]
	v_mfma_f32_16x16x32_bf16 v[46:49], v[134:137], v[204:207], v[46:49]
	v_mfma_f32_16x16x32_bf16 v[42:45], v[142:145], v[204:207], v[42:45]
	v_mfma_f32_16x16x32_bf16 v[30:33], v[134:137], v[222:225], v[30:33]
	v_mfma_f32_16x16x32_bf16 v[26:29], v[142:145], v[222:225], v[26:29]
	v_mfma_f32_16x16x32_bf16 v[14:17], v[134:137], v[230:233], v[14:17]
	v_mfma_f32_16x16x32_bf16 v[10:13], v[142:145], v[230:233], v[10:13]
	s_setprio 0
	s_setprio 1
	v_mfma_f32_16x16x32_bf16 v[50:53], v[146:149], v[176:179], v[50:53]
	v_mfma_f32_16x16x32_bf16 v[54:57], v[168:171], v[176:179], v[54:57]
	v_mfma_f32_16x16x32_bf16 v[34:37], v[146:149], v[186:189], v[34:37]
	v_mfma_f32_16x16x32_bf16 v[38:41], v[168:171], v[186:189], v[38:41]
	v_mfma_f32_16x16x32_bf16 v[18:21], v[146:149], v[218:221], v[18:21]
	v_mfma_f32_16x16x32_bf16 v[22:25], v[168:171], v[218:221], v[22:25]
	v_mfma_f32_16x16x32_bf16 v[2:5], v[146:149], v[226:229], v[2:5]
	v_mfma_f32_16x16x32_bf16 v[6:9], v[168:171], v[226:229], v[6:9]
	v_mfma_f32_16x16x32_bf16 v[50:53], v[150:153], v[180:183], v[50:53]
	v_mfma_f32_16x16x32_bf16 v[54:57], v[172:175], v[180:183], v[54:57]
	v_mfma_f32_16x16x32_bf16 v[34:37], v[150:153], v[204:207], v[34:37]
	v_mfma_f32_16x16x32_bf16 v[38:41], v[172:175], v[204:207], v[38:41]
	v_mfma_f32_16x16x32_bf16 v[18:21], v[150:153], v[222:225], v[18:21]
	v_mfma_f32_16x16x32_bf16 v[22:25], v[172:175], v[222:225], v[22:25]
	v_mfma_f32_16x16x32_bf16 v[2:5], v[150:153], v[230:233], v[2:5]
	v_mfma_f32_16x16x32_bf16 v[6:9], v[172:175], v[230:233], v[6:9]
	s_barrier
	s_setprio 0
	s_add_i32 s73, 0, 0x18000
	v_add_u32_e32 v0, s73, v192
	s_add_i32 s74, 0, 0x1c000
	ds_read_b128 v[130:133], v0
	ds_read_b128 v[134:137], v0 offset:1024
	ds_read_b128 v[138:141], v0 offset:2048
	ds_read_b128 v[142:145], v0 offset:3072
	v_add_u32_e32 v0, s74, v192
	ds_read_b128 v[146:149], v0
	ds_read_b128 v[150:153], v0 offset:1024
	ds_read_b128 v[168:171], v0 offset:2048
	ds_read_b128 v[172:175], v0 offset:3072
	s_add_u32 s48, s48, 0x80000
	s_addc_u32 s49, s49, 0
	s_mov_b32 m0, s79
	v_lshl_add_u64 v[236:237], s[48:49], 0, v[156:157]
	ds_read_b128 v[176:179], v193 offset:32768
	ds_read_b128 v[180:183], v193 offset:33792
	ds_read_b128 v[186:189], v193 offset:34816
	ds_read_b128 v[204:207], v193 offset:35840
	ds_read_b128 v[218:221], v193 offset:36864
	ds_read_b128 v[222:225], v193 offset:37888
	ds_read_b128 v[226:229], v193 offset:38912
	ds_read_b128 v[230:233], v193 offset:39936
	global_load_lds_dwordx4 v[236:237], off
	v_lshl_add_u64 v[236:237], s[48:49], 0, v[160:161]
	s_mov_b32 m0, s80
	s_nop 0
	global_load_lds_dwordx4 v[236:237], off
	s_waitcnt vmcnt(8)
	s_waitcnt lgkmcnt(0)
	s_setprio 1
	s_barrier
	v_mfma_f32_16x16x32_bf16 v[126:129], v[130:133], v[176:179], v[126:129]
	v_mfma_f32_16x16x32_bf16 v[122:125], v[138:141], v[176:179], v[122:125]
	v_mfma_f32_16x16x32_bf16 v[110:113], v[130:133], v[186:189], v[110:113]
	v_mfma_f32_16x16x32_bf16 v[106:109], v[138:141], v[186:189], v[106:109]
	v_mfma_f32_16x16x32_bf16 v[94:97], v[130:133], v[218:221], v[94:97]
	v_mfma_f32_16x16x32_bf16 v[90:93], v[138:141], v[218:221], v[90:93]
	v_mfma_f32_16x16x32_bf16 v[78:81], v[130:133], v[226:229], v[78:81]
	v_mfma_f32_16x16x32_bf16 v[74:77], v[138:141], v[226:229], v[74:77]
	v_mfma_f32_16x16x32_bf16 v[126:129], v[134:137], v[180:183], v[126:129]
	v_mfma_f32_16x16x32_bf16 v[122:125], v[142:145], v[180:183], v[122:125]
	v_mfma_f32_16x16x32_bf16 v[110:113], v[134:137], v[204:207], v[110:113]
	v_mfma_f32_16x16x32_bf16 v[106:109], v[142:145], v[204:207], v[106:109]
	v_mfma_f32_16x16x32_bf16 v[94:97], v[134:137], v[222:225], v[94:97]
	v_mfma_f32_16x16x32_bf16 v[90:93], v[142:145], v[222:225], v[90:93]
	v_mfma_f32_16x16x32_bf16 v[78:81], v[134:137], v[230:233], v[78:81]
	v_mfma_f32_16x16x32_bf16 v[74:77], v[142:145], v[230:233], v[74:77]
	s_setprio 0
	s_setprio 1
	v_mfma_f32_16x16x32_bf16 v[114:117], v[146:149], v[176:179], v[114:117]
	v_mfma_f32_16x16x32_bf16 v[118:121], v[168:171], v[176:179], v[118:121]
	v_mfma_f32_16x16x32_bf16 v[98:101], v[146:149], v[186:189], v[98:101]
	v_mfma_f32_16x16x32_bf16 v[102:105], v[168:171], v[186:189], v[102:105]
	v_mfma_f32_16x16x32_bf16 v[82:85], v[146:149], v[218:221], v[82:85]
	v_mfma_f32_16x16x32_bf16 v[86:89], v[168:171], v[218:221], v[86:89]
	v_mfma_f32_16x16x32_bf16 v[66:69], v[146:149], v[226:229], v[66:69]
	v_mfma_f32_16x16x32_bf16 v[70:73], v[168:171], v[226:229], v[70:73]
	v_mfma_f32_16x16x32_bf16 v[114:117], v[150:153], v[180:183], v[114:117]
	v_mfma_f32_16x16x32_bf16 v[118:121], v[172:175], v[180:183], v[118:121]
	v_mfma_f32_16x16x32_bf16 v[98:101], v[150:153], v[204:207], v[98:101]
	v_mfma_f32_16x16x32_bf16 v[102:105], v[172:175], v[204:207], v[102:105]
	v_mfma_f32_16x16x32_bf16 v[82:85], v[150:153], v[222:225], v[82:85]
	v_mfma_f32_16x16x32_bf16 v[86:89], v[172:175], v[222:225], v[86:89]
	v_mfma_f32_16x16x32_bf16 v[66:69], v[150:153], v[230:233], v[66:69]
	v_mfma_f32_16x16x32_bf16 v[70:73], v[172:175], v[230:233], v[70:73]
	s_barrier
; #define PG8_STAGE(bufoff, gbase, voff) do { _Pragma("unroll") for (int _i = 0; _i < 2; ++_i) \
;         __builtin_amdgcn_global_load_lds((const unsigned*)((const char*)(gbase) + (voff)[_i]), (PG8_LAS unsigned*)(lds + (bufoff) + ldsw + _i * 8192), 16, 0, 0); } while (0)
; #define PG8_LDA(dst, b, h) do { _Pragma("unroll") for (int m = 0; m < 4; ++m) _Pragma("unroll") for (int k = 0; k < 2; ++k) dst[m][k] = *(const PG8_LAS bf16x8*)(lds + PG8_SA(b, h) + aoff + m * 2048 + k * 1024); } while (0)
; #define PG8_MMA(ai, bj, At, Bt) do { __builtin_amdgcn_s_setprio(1); _Pragma("unroll") for (int m = 0; m < 4; ++m) _Pragma("unroll") for (int n = 0; n < 2; ++n) _Pragma("unroll") for (int k = 0; k < 2; ++k) \
;         acc[ai][bj][m][n] = __builtin_amdgcn_mfma_f32_16x16x32_bf16(Bt[n][k], At[m][k], acc[ai][bj][m][n], 0, 0, 0); __builtin_amdgcn_s_setprio(0); } while (0)
; #define PG8_WAIT_V(n) asm volatile("s_waitcnt vmcnt(" #n ")" ::: "memory")
; #define PG8_WAIT_L(n) asm volatile("s_waitcnt lgkmcnt(" #n ")" ::: "memory")
; #define PG8_BAR __builtin_amdgcn_s_barrier()
; #define PG8_SCHED __builtin_amdgcn_sched_barrier(0)
; template <class Epi, class Sched, bool ALIGN_EPI = false, bool SP2 = false>
; __device__ __forceinline__ void gemm_phase(PG8_LAS unsigned char* lds, const Gemm g, const Sched& S, const Epi& E) {
;     ...
;             PG8_LDA(At, 1, 1); PG8_STAGE(PG8_SB(1, 0), b3, voffB); PG8_STAGE(PG8_SB(1, 1), b3 + hstep, voffB); PG8_STAGE(PG8_SA(1, 0), a3, voffA);
;             PG8_WAIT_V(8); PG8_WAIT_L(0); PG8_BAR; PG8_MMA(1, 0, At, B0); PG8_MMA(1, 1, At, B1); PG8_BAR; PG8_SCHED;
;     ...
;         if constexpr (ALIGN_EPI) { if (wr == 0) PG8_BAR; }
	s_setprio 0
	s_add_i32 s48, s73, s76
	v_lshl_add_u64 v[154:155], v[154:155], 0, s[56:57]
	s_mov_b32 m0, s48
	ds_read_b128 v[176:179], v193 offset:49152
	ds_read_b128 v[180:183], v193 offset:50176
	ds_read_b128 v[186:189], v193 offset:51200
	ds_read_b128 v[204:207], v193 offset:52224
	ds_read_b128 v[218:221], v193 offset:53248
	ds_read_b128 v[222:225], v193 offset:54272
	ds_read_b128 v[226:229], v193 offset:55296
	ds_read_b128 v[230:233], v193 offset:56320
	global_load_lds_dwordx4 v[154:155], off
	s_add_i32 m0, s48, 0x2000
	s_add_u32 s44, s44, 0x80080
	v_lshl_add_u64 v[154:155], v[200:201], 0, s[56:57]
	s_addc_u32 s45, s45, 0
	s_add_i32 s48, s74, s76
	global_load_lds_dwordx4 v[154:155], off
	s_nop 0
	s_mov_b32 m0, s48
	s_nop 0
	global_load_lds_dwordx4 v158, s[44:45]
	s_nop 0
	s_add_i32 m0, s48, 0x2000
	s_nop 0
	global_load_lds_dwordx4 v162, s[44:45]
	v_lshl_add_u64 v[154:155], v[202:203], 0, s[56:57]
	s_mov_b32 m0, s88
	s_nop 0
	global_load_lds_dwordx4 v[154:155], off
	v_lshl_add_u64 v[154:155], v[234:235], 0, s[56:57]
	s_mov_b32 m0, s37
	s_nop 0
	global_load_lds_dwordx4 v[154:155], off
	s_waitcnt vmcnt(8)
	s_waitcnt lgkmcnt(0)
	s_setprio 1
	s_barrier
	v_mfma_f32_16x16x32_bf16 v[62:65], v[130:133], v[176:179], v[62:65]
	v_mfma_f32_16x16x32_bf16 v[58:61], v[138:141], v[176:179], v[58:61]
	v_mfma_f32_16x16x32_bf16 v[46:49], v[130:133], v[186:189], v[46:49]
	v_mfma_f32_16x16x32_bf16 v[42:45], v[138:141], v[186:189], v[42:45]
	v_mfma_f32_16x16x32_bf16 v[30:33], v[130:133], v[218:221], v[30:33]
	v_mfma_f32_16x16x32_bf16 v[26:29], v[138:141], v[218:221], v[26:29]
	v_mfma_f32_16x16x32_bf16 v[14:17], v[130:133], v[226:229], v[14:17]
	v_mfma_f32_16x16x32_bf16 v[10:13], v[138:141], v[226:229], v[10:13]
	v_mfma_f32_16x16x32_bf16 v[62:65], v[134:137], v[180:183], v[62:65]
	v_mfma_f32_16x16x32_bf16 v[58:61], v[142:145], v[180:183], v[58:61]
	v_mfma_f32_16x16x32_bf16 v[46:49], v[134:137], v[204:207], v[46:49]
	v_mfma_f32_16x16x32_bf16 v[42:45], v[142:145], v[204:207], v[42:45]
	v_mfma_f32_16x16x32_bf16 v[30:33], v[134:137], v[222:225], v[30:33]
	v_mfma_f32_16x16x32_bf16 v[26:29], v[142:145], v[222:225], v[26:29]
	v_mfma_f32_16x16x32_bf16 v[14:17], v[134:137], v[230:233], v[14:17]
	v_mfma_f32_16x16x32_bf16 v[10:13], v[142:145], v[230:233], v[10:13]
	s_setprio 0
	s_setprio 1
	v_mfma_f32_16x16x32_bf16 v[50:53], v[146:149], v[176:179], v[50:53]
	v_mfma_f32_16x16x32_bf16 v[54:57], v[168:171], v[176:179], v[54:57]
	v_mfma_f32_16x16x32_bf16 v[34:37], v[146:149], v[186:189], v[34:37]
	v_mfma_f32_16x16x32_bf16 v[38:41], v[168:171], v[186:189], v[38:41]
	v_mfma_f32_16x16x32_bf16 v[18:21], v[146:149], v[218:221], v[18:21]
	v_mfma_f32_16x16x32_bf16 v[22:25], v[168:171], v[218:221], v[22:25]
	v_mfma_f32_16x16x32_bf16 v[2:5], v[146:149], v[226:229], v[2:5]
	v_mfma_f32_16x16x32_bf16 v[6:9], v[168:171], v[226:229], v[6:9]
	v_mfma_f32_16x16x32_bf16 v[50:53], v[150:153], v[180:183], v[50:53]
	v_mfma_f32_16x16x32_bf16 v[54:57], v[172:175], v[180:183], v[54:57]
	v_mfma_f32_16x16x32_bf16 v[34:37], v[150:153], v[204:207], v[34:37]
	v_mfma_f32_16x16x32_bf16 v[38:41], v[172:175], v[204:207], v[38:41]
	v_mfma_f32_16x16x32_bf16 v[18:21], v[150:153], v[222:225], v[18:21]
	v_mfma_f32_16x16x32_bf16 v[22:25], v[172:175], v[222:225], v[22:25]
	v_mfma_f32_16x16x32_bf16 v[2:5], v[150:153], v[230:233], v[2:5]
	v_mfma_f32_16x16x32_bf16 v[6:9], v[172:175], v[230:233], v[6:9]
	s_barrier
	s_setprio 0
	s_add_i32 s51, s51, 2
	s_add_u32 s24, s24, 0x100
	s_addc_u32 s25, s25, 0
	s_add_u32 s27, s27, 0x100
	s_addc_u32 s47, s47, 0
	s_cmp_gt_u32 s51, 29
	s_cbranch_scc0 .LBB0_643
	s_and_b64 vcc, exec, s[68:69]
	s_cbranch_vccz .LBB0_646
	s_barrier

; #define PG8_STAGE(bufoff, gbase, voff) do { _Pragma("unroll") for (int _i = 0; _i < 2; ++_i) \
;         __builtin_amdgcn_global_load_lds((const unsigned*)((const char*)(gbase) + (voff)[_i]), (PG8_LAS unsigned*)(lds + (bufoff) + ldsw + _i * 8192), 16, 0, 0); } while (0)
; #define PG8_LDA(dst, b, h) do { _Pragma("unroll") for (int m = 0; m < 4; ++m) _Pragma("unroll") for (int k = 0; k < 2; ++k) dst[m][k] = *(const PG8_LAS bf16x8*)(lds + PG8_SA(b, h) + aoff + m * 2048 + k * 1024); } while (0)
; #define PG8_LDB(dst, b, h) do { _Pragma("unroll") for (int n = 0; n < 2; ++n) _Pragma("unroll") for (int k = 0; k < 2; ++k) dst[n][k] = *(const PG8_LAS bf16x8*)(lds + PG8_SB(b, h) + boff + n * 2048 + k * 1024); } while (0)
; #define PG8_MMA(ai, bj, At, Bt) do { __builtin_amdgcn_s_setprio(1); _Pragma("unroll") for (int m = 0; m < 4; ++m) _Pragma("unroll") for (int n = 0; n < 2; ++n) _Pragma("unroll") for (int k = 0; k < 2; ++k) \
;         acc[ai][bj][m][n] = __builtin_amdgcn_mfma_f32_16x16x32_bf16(Bt[n][k], At[m][k], acc[ai][bj][m][n], 0, 0, 0); __builtin_amdgcn_s_setprio(0); } while (0)
; #define PG8_WAIT_V(n) asm volatile("s_waitcnt vmcnt(" #n ")" ::: "memory")
; #define PG8_BAR __builtin_amdgcn_s_barrier()
; template <class Epi, class Sched, bool ALIGN_EPI = false, bool SP2 = false>
; __device__ __forceinline__ void gemm_phase(PG8_LAS unsigned char* lds, const Gemm g, const Sched& S, const Epi& E) {
;     ...
;         for (int t = 0; t < nt; t += 2) {
;             const bool last = (t == nt - 2);
;             const char* a1 = cA + (size_t)(t + 1) * kstep;
;             const char* a2 = last ? nA : cA + (size_t)(t + 2) * kstep; const char* b2 = last ? nB : cB + (size_t)(t + 2) * kstep;
;             const char* a3 = a2 + kstep; const char* b3 = b2 + kstep;
;             if (last && has_next) S.a_ready(nxt);
;             if constexpr (SP2) {
;             PG8_LDB(B0, 0, 0); PG8_LDB(B1, 0, 1); PG8_SCHED; PG8_LDA(At, 0, 0); PG8_STAGE(PG8_SA(1, 1), a1 + hstep, voffA);
;             PG8_WAIT_V(8); PG8_WAIT_L(0); PG8_BAR; PG8_MMA(0, 0, At, B0); PG8_MMA(0, 1, At, B1); PG8_BAR; PG8_SCHED;
;             PG8_LDA(At, 0, 1); PG8_STAGE(PG8_SB(0, 0), b2, voffB); PG8_STAGE(PG8_SB(0, 1), b2 + hstep, voffB); PG8_STAGE(PG8_SA(0, 0), a2, voffA);
;             PG8_WAIT_V(8); PG8_WAIT_L(0); PG8_BAR; PG8_MMA(1, 0, At, B0); PG8_MMA(1, 1, At, B1); PG8_BAR; PG8_SCHED;
.LBB0_1000:
	s_add_u32 s24, s22, 0x100
	s_addc_u32 s25, s23, 0
	s_add_i32 s59, 0, 0x10000
	s_cmpk_eq_i32 s58, 0x54
	s_cselect_b32 s45, s19, s25
	s_cselect_b32 s44, s18, s24
	s_cselect_b32 s41, s21, s55
	s_cselect_b32 s40, s20, s54
	s_add_i32 s62, 0, 0x14000
	v_add_u32_e32 v152, s59, v163
	v_add_u32_e32 v160, s62, v163
	ds_read_b128 v[130:133], v152
	ds_read_b128 v[134:137], v152 offset:1024
	ds_read_b128 v[138:141], v152 offset:2048
	ds_read_b128 v[152:155], v152 offset:3072
	ds_read_b128 v[156:159], v160
	ds_read_b128 v[166:169], v160 offset:1024
	ds_read_b128 v[170:173], v160 offset:2048
	ds_read_b128 v[174:177], v160 offset:3072
	v_lshl_add_u64 v[160:161], s[22:23], 0, v[148:149]
	s_add_i32 m0, s2, 0xc000
	ds_read_b128 v[178:181], v165
	ds_read_b128 v[182:185], v165 offset:1024
	ds_read_b128 v[186:189], v165 offset:2048
	ds_read_b128 v[190:193], v165 offset:3072
	ds_read_b128 v[204:207], v165 offset:4096
	ds_read_b128 v[218:221], v165 offset:5120
	ds_read_b128 v[222:225], v165 offset:6144
	ds_read_b128 v[226:229], v165 offset:7168
	global_load_lds_dwordx4 v[160:161], off
	v_lshl_add_u64 v[160:161], s[22:23], 0, v[150:151]
	s_add_i32 m0, s2, 0xe000
	s_nop 0
	global_load_lds_dwordx4 v[160:161], off
	s_waitcnt vmcnt(8)
	s_waitcnt lgkmcnt(0)
	s_setprio 1
	s_barrier
	v_mfma_f32_16x16x32_bf16 v[126:129], v[130:133], v[178:181], v[126:129]
	v_mfma_f32_16x16x32_bf16 v[122:125], v[138:141], v[178:181], v[122:125]
	v_mfma_f32_16x16x32_bf16 v[110:113], v[130:133], v[186:189], v[110:113]
	v_mfma_f32_16x16x32_bf16 v[106:109], v[138:141], v[186:189], v[106:109]
	v_mfma_f32_16x16x32_bf16 v[94:97], v[130:133], v[204:207], v[94:97]
	v_mfma_f32_16x16x32_bf16 v[90:93], v[138:141], v[204:207], v[90:93]
	v_mfma_f32_16x16x32_bf16 v[78:81], v[130:133], v[222:225], v[78:81]
	v_mfma_f32_16x16x32_bf16 v[74:77], v[138:141], v[222:225], v[74:77]
	v_mfma_f32_16x16x32_bf16 v[126:129], v[134:137], v[182:185], v[126:129]
	v_mfma_f32_16x16x32_bf16 v[122:125], v[152:155], v[182:185], v[122:125]
	v_mfma_f32_16x16x32_bf16 v[110:113], v[134:137], v[190:193], v[110:113]
	v_mfma_f32_16x16x32_bf16 v[106:109], v[152:155], v[190:193], v[106:109]
	v_mfma_f32_16x16x32_bf16 v[94:97], v[134:137], v[218:221], v[94:97]
	v_mfma_f32_16x16x32_bf16 v[90:93], v[152:155], v[218:221], v[90:93]
	v_mfma_f32_16x16x32_bf16 v[78:81], v[134:137], v[226:229], v[78:81]
	v_mfma_f32_16x16x32_bf16 v[74:77], v[152:155], v[226:229], v[74:77]
	s_setprio 0
	s_setprio 1
	v_mfma_f32_16x16x32_bf16 v[118:121], v[156:159], v[178:181], v[118:121]
	v_mfma_f32_16x16x32_bf16 v[114:117], v[170:173], v[178:181], v[114:117]
	v_mfma_f32_16x16x32_bf16 v[102:105], v[156:159], v[186:189], v[102:105]
	v_mfma_f32_16x16x32_bf16 v[98:101], v[170:173], v[186:189], v[98:101]
	v_mfma_f32_16x16x32_bf16 v[86:89], v[156:159], v[204:207], v[86:89]
	v_mfma_f32_16x16x32_bf16 v[82:85], v[170:173], v[204:207], v[82:85]
	v_mfma_f32_16x16x32_bf16 v[70:73], v[156:159], v[222:225], v[70:73]
	v_mfma_f32_16x16x32_bf16 v[66:69], v[170:173], v[222:225], v[66:69]
	v_mfma_f32_16x16x32_bf16 v[118:121], v[166:169], v[182:185], v[118:121]
	v_mfma_f32_16x16x32_bf16 v[114:117], v[174:177], v[182:185], v[114:117]
	v_mfma_f32_16x16x32_bf16 v[102:105], v[166:169], v[190:193], v[102:105]
	v_mfma_f32_16x16x32_bf16 v[98:101], v[174:177], v[190:193], v[98:101]
	v_mfma_f32_16x16x32_bf16 v[86:89], v[166:169], v[218:221], v[86:89]
	v_mfma_f32_16x16x32_bf16 v[82:85], v[174:177], v[218:221], v[82:85]
	v_mfma_f32_16x16x32_bf16 v[70:73], v[166:169], v[226:229], v[70:73]
	v_mfma_f32_16x16x32_bf16 v[66:69], v[174:177], v[226:229], v[66:69]
	s_barrier
	s_setprio 0
	s_add_i32 s22, s59, s1
	v_lshl_add_u64 v[160:161], s[40:41], 0, v[0:1]
	s_mov_b32 m0, s22
	ds_read_b128 v[178:181], v165 offset:16384
	ds_read_b128 v[182:185], v165 offset:17408
	ds_read_b128 v[186:189], v165 offset:18432
	ds_read_b128 v[190:193], v165 offset:19456
	ds_read_b128 v[204:207], v165 offset:20480
	ds_read_b128 v[218:221], v165 offset:21504
	ds_read_b128 v[222:225], v165 offset:22528
	ds_read_b128 v[226:229], v165 offset:23552
	global_load_lds_dwordx4 v[160:161], off
	s_add_i32 m0, s22, 0x2000
	s_add_u32 s22, s40, 0x160000
	v_lshl_add_u64 v[200:201], s[40:41], 0, v[146:147]
	s_addc_u32 s23, s41, 0
	s_add_i32 s59, s62, s1
	global_load_lds_dwordx4 v[200:201], off
	s_nop 0
	s_mov_b32 m0, s59
	v_lshl_add_u64 v[230:231], s[44:45], 0, v[144:145]
	global_load_lds_dwordx4 v0, s[22:23]
	s_nop 0
	s_add_i32 m0, s59, 0x2000
	s_nop 0
	global_load_lds_dwordx4 v146, s[22:23]
	v_lshl_add_u64 v[202:203], s[44:45], 0, v[142:143]
	s_mov_b32 m0, s2
	s_nop 0
	global_load_lds_dwordx4 v[202:203], off
	s_mov_b32 m0, s3
	s_nop 0
	global_load_lds_dwordx4 v[230:231], off
	s_waitcnt vmcnt(8)
	s_waitcnt lgkmcnt(0)
	s_setprio 1
	s_barrier
; #define PG8_STAGE(bufoff, gbase, voff) do { _Pragma("unroll") for (int _i = 0; _i < 2; ++_i) \
;         __builtin_amdgcn_global_load_lds((const unsigned*)((const char*)(gbase) + (voff)[_i]), (PG8_LAS unsigned*)(lds + (bufoff) + ldsw + _i * 8192), 16, 0, 0); } while (0)
; #define PG8_LDA(dst, b, h) do { _Pragma("unroll") for (int m = 0; m < 4; ++m) _Pragma("unroll") for (int k = 0; k < 2; ++k) dst[m][k] = *(const PG8_LAS bf16x8*)(lds + PG8_SA(b, h) + aoff + m * 2048 + k * 1024); } while (0)
; #define PG8_LDB(dst, b, h) do { _Pragma("unroll") for (int n = 0; n < 2; ++n) _Pragma("unroll") for (int k = 0; k < 2; ++k) dst[n][k] = *(const PG8_LAS bf16x8*)(lds + PG8_SB(b, h) + boff + n * 2048 + k * 1024); } while (0)
; #define PG8_MMA(ai, bj, At, Bt) do { __builtin_amdgcn_s_setprio(1); _Pragma("unroll") for (int m = 0; m < 4; ++m) _Pragma("unroll") for (int n = 0; n < 2; ++n) _Pragma("unroll") for (int k = 0; k < 2; ++k) \
;         acc[ai][bj][m][n] = __builtin_amdgcn_mfma_f32_16x16x32_bf16(Bt[n][k], At[m][k], acc[ai][bj][m][n], 0, 0, 0); __builtin_amdgcn_s_setprio(0); } while (0)
; #define PG8_WAIT_V(n) asm volatile("s_waitcnt vmcnt(" #n ")" ::: "memory")
; #define PG8_WAIT_L(n) asm volatile("s_waitcnt lgkmcnt(" #n ")" ::: "memory")
; #define PG8_BAR __builtin_amdgcn_s_barrier()
; #define PG8_SCHED __builtin_amdgcn_sched_barrier(0)
; template <class Epi, class Sched, bool ALIGN_EPI = false, bool SP2 = false>
; __device__ __forceinline__ void gemm_phase(PG8_LAS unsigned char* lds, const Gemm g, const Sched& S, const Epi& E) {
;     ...
;             PG8_WAIT_V(8); PG8_WAIT_L(0); PG8_BAR; PG8_MMA(0, 0, At, B0); PG8_MMA(0, 1, At, B1); PG8_BAR; PG8_SCHED;
;             PG8_LDA(At, 0, 1); PG8_STAGE(PG8_SB(0, 0), b2, voffB); PG8_STAGE(PG8_SB(0, 1), b2 + hstep, voffB); PG8_STAGE(PG8_SA(0, 0), a2, voffA);
;             PG8_WAIT_V(8); PG8_WAIT_L(0); PG8_BAR; PG8_MMA(1, 0, At, B0); PG8_MMA(1, 1, At, B1); PG8_BAR; PG8_SCHED;
;             PG8_LDB(B0, 1, 0); PG8_LDB(B1, 1, 1); PG8_SCHED; PG8_LDA(At, 1, 0); PG8_STAGE(PG8_SA(0, 1), a2 + hstep, voffA);
;             PG8_WAIT_V(8); PG8_WAIT_L(0); PG8_BAR; PG8_MMA(0, 0, At, B0); PG8_MMA(0, 1, At, B1); PG8_BAR; PG8_SCHED;
	v_mfma_f32_16x16x32_bf16 v[62:65], v[130:133], v[178:181], v[62:65]
	v_mfma_f32_16x16x32_bf16 v[58:61], v[138:141], v[178:181], v[58:61]
	v_mfma_f32_16x16x32_bf16 v[46:49], v[130:133], v[186:189], v[46:49]
	v_mfma_f32_16x16x32_bf16 v[42:45], v[138:141], v[186:189], v[42:45]
	v_mfma_f32_16x16x32_bf16 v[30:33], v[130:133], v[204:207], v[30:33]
	v_mfma_f32_16x16x32_bf16 v[26:29], v[138:141], v[204:207], v[26:29]
	v_mfma_f32_16x16x32_bf16 v[14:17], v[130:133], v[222:225], v[14:17]
	v_mfma_f32_16x16x32_bf16 v[10:13], v[138:141], v[222:225], v[10:13]
	v_mfma_f32_16x16x32_bf16 v[62:65], v[134:137], v[182:185], v[62:65]
	v_mfma_f32_16x16x32_bf16 v[58:61], v[152:155], v[182:185], v[58:61]
	v_mfma_f32_16x16x32_bf16 v[46:49], v[134:137], v[190:193], v[46:49]
	v_mfma_f32_16x16x32_bf16 v[42:45], v[152:155], v[190:193], v[42:45]
	v_mfma_f32_16x16x32_bf16 v[30:33], v[134:137], v[218:221], v[30:33]
	v_mfma_f32_16x16x32_bf16 v[26:29], v[152:155], v[218:221], v[26:29]
	v_mfma_f32_16x16x32_bf16 v[14:17], v[134:137], v[226:229], v[14:17]
	v_mfma_f32_16x16x32_bf16 v[10:13], v[152:155], v[226:229], v[10:13]
	s_setprio 0
	s_setprio 1
	v_mfma_f32_16x16x32_bf16 v[54:57], v[156:159], v[178:181], v[54:57]
	v_mfma_f32_16x16x32_bf16 v[50:53], v[170:173], v[178:181], v[50:53]
	v_mfma_f32_16x16x32_bf16 v[38:41], v[156:159], v[186:189], v[38:41]
	v_mfma_f32_16x16x32_bf16 v[34:37], v[170:173], v[186:189], v[34:37]
	v_mfma_f32_16x16x32_bf16 v[22:25], v[156:159], v[204:207], v[22:25]
	v_mfma_f32_16x16x32_bf16 v[18:21], v[170:173], v[204:207], v[18:21]
	v_mfma_f32_16x16x32_bf16 v[6:9], v[156:159], v[222:225], v[6:9]
	v_mfma_f32_16x16x32_bf16 v[2:5], v[170:173], v[222:225], v[2:5]
	v_mfma_f32_16x16x32_bf16 v[54:57], v[166:169], v[182:185], v[54:57]
	v_mfma_f32_16x16x32_bf16 v[50:53], v[174:177], v[182:185], v[50:53]
	v_mfma_f32_16x16x32_bf16 v[38:41], v[166:169], v[190:193], v[38:41]
	v_mfma_f32_16x16x32_bf16 v[34:37], v[174:177], v[190:193], v[34:37]
	v_mfma_f32_16x16x32_bf16 v[22:25], v[166:169], v[218:221], v[22:25]
	v_mfma_f32_16x16x32_bf16 v[18:21], v[174:177], v[218:221], v[18:21]
	v_mfma_f32_16x16x32_bf16 v[6:9], v[166:169], v[226:229], v[6:9]
	v_mfma_f32_16x16x32_bf16 v[2:5], v[174:177], v[226:229], v[2:5]
	s_barrier
	s_setprio 0
	s_add_i32 s59, 0, 0x18000
	s_add_i32 s62, 0, 0x1c000
	v_add_u32_e32 v152, s59, v163
	v_add_u32_e32 v174, s62, v163
	ds_read_b128 v[130:133], v152
	ds_read_b128 v[134:137], v152 offset:1024
	ds_read_b128 v[138:141], v152 offset:2048
	ds_read_b128 v[152:155], v152 offset:3072
	ds_read_b128 v[156:159], v174
	ds_read_b128 v[166:169], v174 offset:1024
	ds_read_b128 v[170:173], v174 offset:2048
	ds_read_b128 v[174:177], v174 offset:3072
	s_add_u32 s22, s44, 0x160000
	s_addc_u32 s23, s45, 0
	s_mov_b32 m0, s10
	v_lshl_add_u64 v[232:233], s[22:23], 0, v[142:143]
	ds_read_b128 v[178:181], v165 offset:32768
	ds_read_b128 v[182:185], v165 offset:33792
	ds_read_b128 v[186:189], v165 offset:34816
	ds_read_b128 v[190:193], v165 offset:35840
	ds_read_b128 v[204:207], v165 offset:36864
	ds_read_b128 v[218:221], v165 offset:37888
	ds_read_b128 v[222:225], v165 offset:38912
	ds_read_b128 v[226:229], v165 offset:39936
	global_load_lds_dwordx4 v[232:233], off
	v_lshl_add_u64 v[232:233], s[22:23], 0, v[144:145]
	s_mov_b32 m0, s11
	s_nop 0
	global_load_lds_dwordx4 v[232:233], off
	s_waitcnt vmcnt(8)
	s_waitcnt lgkmcnt(0)
	s_setprio 1
	s_barrier
	v_mfma_f32_16x16x32_bf16 v[126:129], v[130:133], v[178:181], v[126:129]
	v_mfma_f32_16x16x32_bf16 v[122:125], v[138:141], v[178:181], v[122:125]
	v_mfma_f32_16x16x32_bf16 v[110:113], v[130:133], v[186:189], v[110:113]
	v_mfma_f32_16x16x32_bf16 v[106:109], v[138:141], v[186:189], v[106:109]
	v_mfma_f32_16x16x32_bf16 v[94:97], v[130:133], v[204:207], v[94:97]
	v_mfma_f32_16x16x32_bf16 v[90:93], v[138:141], v[204:207], v[90:93]
	v_mfma_f32_16x16x32_bf16 v[78:81], v[130:133], v[222:225], v[78:81]
	v_mfma_f32_16x16x32_bf16 v[74:77], v[138:141], v[222:225], v[74:77]
	v_mfma_f32_16x16x32_bf16 v[126:129], v[134:137], v[182:185], v[126:129]
	v_mfma_f32_16x16x32_bf16 v[122:125], v[152:155], v[182:185], v[122:125]
	v_mfma_f32_16x16x32_bf16 v[110:113], v[134:137], v[190:193], v[110:113]
	v_mfma_f32_16x16x32_bf16 v[106:109], v[152:155], v[190:193], v[106:109]
	v_mfma_f32_16x16x32_bf16 v[94:97], v[134:137], v[218:221], v[94:97]
	v_mfma_f32_16x16x32_bf16 v[90:93], v[152:155], v[218:221], v[90:93]
	v_mfma_f32_16x16x32_bf16 v[78:81], v[134:137], v[226:229], v[78:81]
	v_mfma_f32_16x16x32_bf16 v[74:77], v[152:155], v[226:229], v[74:77]
	s_setprio 0
	s_setprio 1
	v_mfma_f32_16x16x32_bf16 v[118:121], v[156:159], v[178:181], v[118:121]
	v_mfma_f32_16x16x32_bf16 v[114:117], v[170:173], v[178:181], v[114:117]
	v_mfma_f32_16x16x32_bf16 v[102:105], v[156:159], v[186:189], v[102:105]
	v_mfma_f32_16x16x32_bf16 v[98:101], v[170:173], v[186:189], v[98:101]
	v_mfma_f32_16x16x32_bf16 v[86:89], v[156:159], v[204:207], v[86:89]
	v_mfma_f32_16x16x32_bf16 v[82:85], v[170:173], v[204:207], v[82:85]
	v_mfma_f32_16x16x32_bf16 v[70:73], v[156:159], v[222:225], v[70:73]
	v_mfma_f32_16x16x32_bf16 v[66:69], v[170:173], v[222:225], v[66:69]
	v_mfma_f32_16x16x32_bf16 v[118:121], v[166:169], v[182:185], v[118:121]
	v_mfma_f32_16x16x32_bf16 v[114:117], v[174:177], v[182:185], v[114:117]
	v_mfma_f32_16x16x32_bf16 v[102:105], v[166:169], v[190:193], v[102:105]
	v_mfma_f32_16x16x32_bf16 v[98:101], v[174:177], v[190:193], v[98:101]
	v_mfma_f32_16x16x32_bf16 v[86:89], v[166:169], v[218:221], v[86:89]
	v_mfma_f32_16x16x32_bf16 v[82:85], v[174:177], v[218:221], v[82:85]
	v_mfma_f32_16x16x32_bf16 v[70:73], v[166:169], v[226:229], v[70:73]
	v_mfma_f32_16x16x32_bf16 v[66:69], v[174:177], v[226:229], v[66:69]
	s_barrier
; #define PG8_STAGE(bufoff, gbase, voff) do { _Pragma("unroll") for (int _i = 0; _i < 2; ++_i) \
;         __builtin_amdgcn_global_load_lds((const unsigned*)((const char*)(gbase) + (voff)[_i]), (PG8_LAS unsigned*)(lds + (bufoff) + ldsw + _i * 8192), 16, 0, 0); } while (0)
; #define PG8_LDA(dst, b, h) do { _Pragma("unroll") for (int m = 0; m < 4; ++m) _Pragma("unroll") for (int k = 0; k < 2; ++k) dst[m][k] = *(const PG8_LAS bf16x8*)(lds + PG8_SA(b, h) + aoff + m * 2048 + k * 1024); } while (0)
; #define PG8_MMA(ai, bj, At, Bt) do { __builtin_amdgcn_s_setprio(1); _Pragma("unroll") for (int m = 0; m < 4; ++m) _Pragma("unroll") for (int n = 0; n < 2; ++n) _Pragma("unroll") for (int k = 0; k < 2; ++k) \
;         acc[ai][bj][m][n] = __builtin_amdgcn_mfma_f32_16x16x32_bf16(Bt[n][k], At[m][k], acc[ai][bj][m][n], 0, 0, 0); __builtin_amdgcn_s_setprio(0); } while (0)
; #define PG8_WAIT_V(n) asm volatile("s_waitcnt vmcnt(" #n ")" ::: "memory")
; #define PG8_WAIT_L(n) asm volatile("s_waitcnt lgkmcnt(" #n ")" ::: "memory")
; #define PG8_BAR __builtin_amdgcn_s_barrier()
; #define PG8_SCHED __builtin_amdgcn_sched_barrier(0)
; template <class Epi, class Sched, bool ALIGN_EPI = false, bool SP2 = false>
; __device__ __forceinline__ void gemm_phase(PG8_LAS unsigned char* lds, const Gemm g, const Sched& S, const Epi& E) {
;     ...
;         for (int t = 0; t < nt; t += 2) {
;             const bool last = (t == nt - 2);
;             const char* a1 = cA + (size_t)(t + 1) * kstep;
;             const char* a2 = last ? nA : cA + (size_t)(t + 2) * kstep; const char* b2 = last ? nB : cB + (size_t)(t + 2) * kstep;
;             const char* a3 = a2 + kstep; const char* b3 = b2 + kstep;
;             if (last && has_next) S.a_ready(nxt);
;     ...
;             PG8_LDA(At, 1, 1); PG8_STAGE(PG8_SB(1, 0), b3, voffB); PG8_STAGE(PG8_SB(1, 1), b3 + hstep, voffB); PG8_STAGE(PG8_SA(1, 0), a3, voffA);
;             PG8_WAIT_V(8); PG8_WAIT_L(0); PG8_BAR; PG8_MMA(1, 0, At, B0); PG8_MMA(1, 1, At, B1); PG8_BAR; PG8_SCHED;
;     ...
;         if constexpr (ALIGN_EPI) { if (wr == 0) PG8_BAR; }
	s_setprio 0
	s_add_i32 s22, s59, s1
	v_lshl_add_u64 v[160:161], v[160:161], 0, s[56:57]
	s_mov_b32 m0, s22
	ds_read_b128 v[178:181], v165 offset:49152
	ds_read_b128 v[182:185], v165 offset:50176
	ds_read_b128 v[186:189], v165 offset:51200
	ds_read_b128 v[190:193], v165 offset:52224
	ds_read_b128 v[204:207], v165 offset:53248
	ds_read_b128 v[218:221], v165 offset:54272
	ds_read_b128 v[222:225], v165 offset:55296
	ds_read_b128 v[226:229], v165 offset:56320
	global_load_lds_dwordx4 v[160:161], off
	s_add_i32 m0, s22, 0x2000
	s_add_u32 s22, s40, 0x160080
	v_lshl_add_u64 v[160:161], v[200:201], 0, s[56:57]
	s_addc_u32 s23, s41, 0
	s_add_i32 s40, s62, s1
	global_load_lds_dwordx4 v[160:161], off
	s_nop 0
	s_mov_b32 m0, s40
	s_nop 0
	global_load_lds_dwordx4 v0, s[22:23]
	s_nop 0
	s_add_i32 m0, s40, 0x2000
	s_nop 0
	global_load_lds_dwordx4 v146, s[22:23]
	v_lshl_add_u64 v[160:161], v[202:203], 0, s[56:57]
	s_mov_b32 m0, s37
	s_nop 0
	global_load_lds_dwordx4 v[160:161], off
	v_lshl_add_u64 v[160:161], v[230:231], 0, s[56:57]
	s_mov_b32 m0, s46
	s_nop 0
	global_load_lds_dwordx4 v[160:161], off
	s_waitcnt vmcnt(8)
	s_waitcnt lgkmcnt(0)
	s_setprio 1
	s_barrier
	v_mfma_f32_16x16x32_bf16 v[62:65], v[130:133], v[178:181], v[62:65]
	v_mfma_f32_16x16x32_bf16 v[58:61], v[138:141], v[178:181], v[58:61]
	v_mfma_f32_16x16x32_bf16 v[46:49], v[130:133], v[186:189], v[46:49]
	v_mfma_f32_16x16x32_bf16 v[42:45], v[138:141], v[186:189], v[42:45]
	v_mfma_f32_16x16x32_bf16 v[30:33], v[130:133], v[204:207], v[30:33]
	v_mfma_f32_16x16x32_bf16 v[26:29], v[138:141], v[204:207], v[26:29]
	v_mfma_f32_16x16x32_bf16 v[14:17], v[130:133], v[222:225], v[14:17]
	v_mfma_f32_16x16x32_bf16 v[10:13], v[138:141], v[222:225], v[10:13]
	v_mfma_f32_16x16x32_bf16 v[62:65], v[134:137], v[182:185], v[62:65]
	v_mfma_f32_16x16x32_bf16 v[58:61], v[152:155], v[182:185], v[58:61]
	v_mfma_f32_16x16x32_bf16 v[46:49], v[134:137], v[190:193], v[46:49]
	v_mfma_f32_16x16x32_bf16 v[42:45], v[152:155], v[190:193], v[42:45]
	v_mfma_f32_16x16x32_bf16 v[30:33], v[134:137], v[218:221], v[30:33]
	v_mfma_f32_16x16x32_bf16 v[26:29], v[152:155], v[218:221], v[26:29]
	v_mfma_f32_16x16x32_bf16 v[14:17], v[134:137], v[226:229], v[14:17]
	v_mfma_f32_16x16x32_bf16 v[10:13], v[152:155], v[226:229], v[10:13]
	s_setprio 0
	s_setprio 1
	v_mfma_f32_16x16x32_bf16 v[54:57], v[156:159], v[178:181], v[54:57]
	v_mfma_f32_16x16x32_bf16 v[50:53], v[170:173], v[178:181], v[50:53]
	v_mfma_f32_16x16x32_bf16 v[38:41], v[156:159], v[186:189], v[38:41]
	v_mfma_f32_16x16x32_bf16 v[34:37], v[170:173], v[186:189], v[34:37]
	v_mfma_f32_16x16x32_bf16 v[22:25], v[156:159], v[204:207], v[22:25]
	v_mfma_f32_16x16x32_bf16 v[18:21], v[170:173], v[204:207], v[18:21]
	v_mfma_f32_16x16x32_bf16 v[6:9], v[156:159], v[222:225], v[6:9]
	v_mfma_f32_16x16x32_bf16 v[2:5], v[170:173], v[222:225], v[2:5]
	v_mfma_f32_16x16x32_bf16 v[54:57], v[166:169], v[182:185], v[54:57]
	v_mfma_f32_16x16x32_bf16 v[50:53], v[174:177], v[182:185], v[50:53]
	v_mfma_f32_16x16x32_bf16 v[38:41], v[166:169], v[190:193], v[38:41]
	v_mfma_f32_16x16x32_bf16 v[34:37], v[174:177], v[190:193], v[34:37]
	v_mfma_f32_16x16x32_bf16 v[22:25], v[166:169], v[218:221], v[22:25]
	v_mfma_f32_16x16x32_bf16 v[18:21], v[174:177], v[218:221], v[18:21]
	v_mfma_f32_16x16x32_bf16 v[6:9], v[166:169], v[226:229], v[6:9]
	v_mfma_f32_16x16x32_bf16 v[2:5], v[174:177], v[226:229], v[2:5]
	s_barrier
	s_setprio 0
	s_add_i32 s58, s58, 2
	s_add_u32 s54, s54, 0x100
	s_addc_u32 s55, s55, 0
	s_cmpk_gt_u32 s58, 0x55
	s_mov_b64 s[22:23], s[24:25]
	s_cbranch_scc0 .LBB0_1000
	s_and_b64 vcc, exec, s[16:17]
	s_cbranch_vccz .LBB0_1003
	s_barrier

; #define PG8_STAGE(bufoff, gbase, voff) do { _Pragma("unroll") for (int _i = 0; _i < 2; ++_i) \
;         __builtin_amdgcn_global_load_lds((const unsigned*)((const char*)(gbase) + (voff)[_i]), (PG8_LAS unsigned*)(lds + (bufoff) + ldsw + _i * 8192), 16, 0, 0); } while (0)
; #define PG8_LDA(dst, b, h) do { _Pragma("unroll") for (int m = 0; m < 4; ++m) _Pragma("unroll") for (int k = 0; k < 2; ++k) dst[m][k] = *(const PG8_LAS bf16x8*)(lds + PG8_SA(b, h) + aoff + m * 2048 + k * 1024); } while (0)
; #define PG8_LDB(dst, b, h) do { _Pragma("unroll") for (int n = 0; n < 2; ++n) _Pragma("unroll") for (int k = 0; k < 2; ++k) dst[n][k] = *(const PG8_LAS bf16x8*)(lds + PG8_SB(b, h) + boff + n * 2048 + k * 1024); } while (0)
; #define PG8_MMA(ai, bj, At, Bt) do { __builtin_amdgcn_s_setprio(1); _Pragma("unroll") for (int m = 0; m < 4; ++m) _Pragma("unroll") for (int n = 0; n < 2; ++n) _Pragma("unroll") for (int k = 0; k < 2; ++k) \
;         acc[ai][bj][m][n] = __builtin_amdgcn_mfma_f32_16x16x32_bf16(Bt[n][k], At[m][k], acc[ai][bj][m][n], 0, 0, 0); __builtin_amdgcn_s_setprio(0); } while (0)
; #define PG8_WAIT_V(n) asm volatile("s_waitcnt vmcnt(" #n ")" ::: "memory")
; #define PG8_BAR __builtin_amdgcn_s_barrier()
; template <class Epi, class Sched, bool ALIGN_EPI = false, bool SP2 = false>
; __device__ __forceinline__ void gemm_phase(PG8_LAS unsigned char* lds, const Gemm g, const Sched& S, const Epi& E) {
;     ...
;         for (int t = 0; t < nt; t += 2) {
;             const bool last = (t == nt - 2);
;             const char* a1 = cA + (size_t)(t + 1) * kstep;
;             const char* a2 = last ? nA : cA + (size_t)(t + 2) * kstep; const char* b2 = last ? nB : cB + (size_t)(t + 2) * kstep;
;             const char* a3 = a2 + kstep; const char* b3 = b2 + kstep;
;             if (last && has_next) S.a_ready(nxt);
;             if constexpr (SP2) {
;             PG8_LDB(B0, 0, 0); PG8_LDB(B1, 0, 1); PG8_SCHED; PG8_LDA(At, 0, 0); PG8_STAGE(PG8_SA(1, 1), a1 + hstep, voffA);
;             PG8_WAIT_V(8); PG8_WAIT_L(0); PG8_BAR; PG8_MMA(0, 0, At, B0); PG8_MMA(0, 1, At, B1); PG8_BAR; PG8_SCHED;
;             PG8_LDA(At, 0, 1); PG8_STAGE(PG8_SB(0, 0), b2, voffB); PG8_STAGE(PG8_SB(0, 1), b2 + hstep, voffB); PG8_STAGE(PG8_SA(0, 0), a2, voffA);
;             PG8_WAIT_V(8); PG8_WAIT_L(0); PG8_BAR; PG8_MMA(1, 0, At, B0); PG8_MMA(1, 1, At, B1); PG8_BAR; PG8_SCHED;
.LBB0_1027:
	s_add_u32 s20, s18, 0x100
	s_addc_u32 s21, s19, 0
	s_cmp_lg_u32 s38, 18
	s_cselect_b32 s22, s20, 0
	s_cselect_b32 s23, s21, 0
	s_add_u32 s24, s16, s22
	s_addc_u32 s25, s17, s23
	s_add_i32 s39, 0, 0x10000
	s_add_u32 s22, s14, s22
	s_addc_u32 s23, s15, s23
	s_add_i32 s40, 0, 0x14000
	v_add_u32_e32 v156, s39, v142
	v_add_u32_e32 v172, s40, v142
	ds_read_b128 v[144:147], v156
	ds_read_b128 v[148:151], v156 offset:1024
	ds_read_b128 v[152:155], v156 offset:2048
	ds_read_b128 v[156:159], v156 offset:3072
	ds_read_b128 v[160:163], v172
	ds_read_b128 v[164:167], v172 offset:1024
	ds_read_b128 v[168:171], v172 offset:2048
	ds_read_b128 v[172:175], v172 offset:3072
	v_lshl_add_u64 v[192:193], v[138:139], 0, s[18:19]
	s_add_i32 m0, s3, 0xc000
	ds_read_b128 v[176:179], v143
	ds_read_b128 v[180:183], v143 offset:1024
	ds_read_b128 v[184:187], v143 offset:2048
	ds_read_b128 v[188:191], v143 offset:3072
	ds_read_b128 v[204:207], v143 offset:4096
	ds_read_b128 v[218:221], v143 offset:5120
	ds_read_b128 v[222:225], v143 offset:6144
	ds_read_b128 v[226:229], v143 offset:7168
	global_load_lds_dwordx4 v[192:193], off
	v_lshl_add_u64 v[192:193], v[140:141], 0, s[18:19]
	s_add_i32 m0, s3, 0xe000
	s_nop 0
	global_load_lds_dwordx4 v[192:193], off
	s_waitcnt vmcnt(8)
	s_waitcnt lgkmcnt(0)
	s_setprio 1
	s_barrier
	v_mfma_f32_16x16x32_bf16 v[58:61], v[144:147], v[176:179], v[58:61]
	v_mfma_f32_16x16x32_bf16 v[62:65], v[152:155], v[176:179], v[62:65]
	v_mfma_f32_16x16x32_bf16 v[42:45], v[144:147], v[184:187], v[42:45]
	v_mfma_f32_16x16x32_bf16 v[46:49], v[152:155], v[184:187], v[46:49]
	v_mfma_f32_16x16x32_bf16 v[26:29], v[144:147], v[204:207], v[26:29]
	v_mfma_f32_16x16x32_bf16 v[30:33], v[152:155], v[204:207], v[30:33]
	v_mfma_f32_16x16x32_bf16 v[10:13], v[144:147], v[222:225], v[10:13]
	v_mfma_f32_16x16x32_bf16 v[14:17], v[152:155], v[222:225], v[14:17]
	v_mfma_f32_16x16x32_bf16 v[58:61], v[148:151], v[180:183], v[58:61]
	v_mfma_f32_16x16x32_bf16 v[62:65], v[156:159], v[180:183], v[62:65]
	v_mfma_f32_16x16x32_bf16 v[42:45], v[148:151], v[188:191], v[42:45]
	v_mfma_f32_16x16x32_bf16 v[46:49], v[156:159], v[188:191], v[46:49]
	v_mfma_f32_16x16x32_bf16 v[26:29], v[148:151], v[218:221], v[26:29]
	v_mfma_f32_16x16x32_bf16 v[30:33], v[156:159], v[218:221], v[30:33]
	v_mfma_f32_16x16x32_bf16 v[10:13], v[148:151], v[226:229], v[10:13]
	v_mfma_f32_16x16x32_bf16 v[14:17], v[156:159], v[226:229], v[14:17]
	s_setprio 0
	s_setprio 1
	v_mfma_f32_16x16x32_bf16 v[50:53], v[160:163], v[176:179], v[50:53]
	v_mfma_f32_16x16x32_bf16 v[54:57], v[168:171], v[176:179], v[54:57]
	v_mfma_f32_16x16x32_bf16 v[34:37], v[160:163], v[184:187], v[34:37]
	v_mfma_f32_16x16x32_bf16 v[38:41], v[168:171], v[184:187], v[38:41]
	v_mfma_f32_16x16x32_bf16 v[18:21], v[160:163], v[204:207], v[18:21]
	v_mfma_f32_16x16x32_bf16 v[22:25], v[168:171], v[204:207], v[22:25]
	v_mfma_f32_16x16x32_bf16 v[2:5], v[160:163], v[222:225], v[2:5]
	v_mfma_f32_16x16x32_bf16 v[6:9], v[168:171], v[222:225], v[6:9]
	v_mfma_f32_16x16x32_bf16 v[50:53], v[164:167], v[180:183], v[50:53]
	v_mfma_f32_16x16x32_bf16 v[54:57], v[172:175], v[180:183], v[54:57]
	v_mfma_f32_16x16x32_bf16 v[34:37], v[164:167], v[188:191], v[34:37]
	v_mfma_f32_16x16x32_bf16 v[38:41], v[172:175], v[188:191], v[38:41]
	v_mfma_f32_16x16x32_bf16 v[18:21], v[164:167], v[218:221], v[18:21]
	v_mfma_f32_16x16x32_bf16 v[22:25], v[172:175], v[218:221], v[22:25]
	v_mfma_f32_16x16x32_bf16 v[2:5], v[164:167], v[226:229], v[2:5]
	v_mfma_f32_16x16x32_bf16 v[6:9], v[172:175], v[226:229], v[6:9]
	s_barrier
	s_setprio 0
	s_add_i32 s18, s39, s2
	v_lshl_add_u64 v[192:193], s[22:23], 0, v[0:1]
	s_mov_b32 m0, s18
	ds_read_b128 v[176:179], v143 offset:16384
	ds_read_b128 v[180:183], v143 offset:17408
	ds_read_b128 v[184:187], v143 offset:18432
	ds_read_b128 v[188:191], v143 offset:19456
	ds_read_b128 v[204:207], v143 offset:20480
	ds_read_b128 v[218:221], v143 offset:21504
	ds_read_b128 v[222:225], v143 offset:22528
	ds_read_b128 v[226:229], v143 offset:23552
	global_load_lds_dwordx4 v[192:193], off
	s_add_i32 m0, s18, 0x2000
	s_add_u32 s18, s22, 0x160000
	v_lshl_add_u64 v[200:201], s[22:23], 0, v[136:137]
	s_addc_u32 s19, s23, 0
	s_add_i32 s39, s40, s2
	global_load_lds_dwordx4 v[200:201], off
	s_nop 0
	s_mov_b32 m0, s39
	v_lshl_add_u64 v[230:231], s[24:25], 0, v[134:135]
	global_load_lds_dwordx4 v0, s[18:19]
	s_nop 0
	s_add_i32 m0, s39, 0x2000
	s_nop 0
	global_load_lds_dwordx4 v136, s[18:19]
	v_lshl_add_u64 v[202:203], s[24:25], 0, v[132:133]
	s_mov_b32 m0, s3
	s_nop 0
	global_load_lds_dwordx4 v[202:203], off
	s_mov_b32 m0, s10
	s_nop 0
	global_load_lds_dwordx4 v[230:231], off
	s_waitcnt vmcnt(8)
	s_waitcnt lgkmcnt(0)
	s_setprio 1
	s_barrier
; #define PG8_STAGE(bufoff, gbase, voff) do { _Pragma("unroll") for (int _i = 0; _i < 2; ++_i) \
;         __builtin_amdgcn_global_load_lds((const unsigned*)((const char*)(gbase) + (voff)[_i]), (PG8_LAS unsigned*)(lds + (bufoff) + ldsw + _i * 8192), 16, 0, 0); } while (0)
; #define PG8_LDA(dst, b, h) do { _Pragma("unroll") for (int m = 0; m < 4; ++m) _Pragma("unroll") for (int k = 0; k < 2; ++k) dst[m][k] = *(const PG8_LAS bf16x8*)(lds + PG8_SA(b, h) + aoff + m * 2048 + k * 1024); } while (0)
; #define PG8_LDB(dst, b, h) do { _Pragma("unroll") for (int n = 0; n < 2; ++n) _Pragma("unroll") for (int k = 0; k < 2; ++k) dst[n][k] = *(const PG8_LAS bf16x8*)(lds + PG8_SB(b, h) + boff + n * 2048 + k * 1024); } while (0)
; #define PG8_MMA(ai, bj, At, Bt) do { __builtin_amdgcn_s_setprio(1); _Pragma("unroll") for (int m = 0; m < 4; ++m) _Pragma("unroll") for (int n = 0; n < 2; ++n) _Pragma("unroll") for (int k = 0; k < 2; ++k) \
;         acc[ai][bj][m][n] = __builtin_amdgcn_mfma_f32_16x16x32_bf16(Bt[n][k], At[m][k], acc[ai][bj][m][n], 0, 0, 0); __builtin_amdgcn_s_setprio(0); } while (0)
; #define PG8_WAIT_V(n) asm volatile("s_waitcnt vmcnt(" #n ")" ::: "memory")
; #define PG8_WAIT_L(n) asm volatile("s_waitcnt lgkmcnt(" #n ")" ::: "memory")
; #define PG8_BAR __builtin_amdgcn_s_barrier()
; #define PG8_SCHED __builtin_amdgcn_sched_barrier(0)
; template <class Epi, class Sched, bool ALIGN_EPI = false, bool SP2 = false>
; __device__ __forceinline__ void gemm_phase(PG8_LAS unsigned char* lds, const Gemm g, const Sched& S, const Epi& E) {
;     ...
;             PG8_WAIT_V(8); PG8_WAIT_L(0); PG8_BAR; PG8_MMA(1, 0, At, B0); PG8_MMA(1, 1, At, B1); PG8_BAR; PG8_SCHED;
;             PG8_LDB(B0, 1, 0); PG8_LDB(B1, 1, 1); PG8_SCHED; PG8_LDA(At, 1, 0); PG8_STAGE(PG8_SA(0, 1), a2 + hstep, voffA);
;             PG8_WAIT_V(8); PG8_WAIT_L(0); PG8_BAR; PG8_MMA(0, 0, At, B0); PG8_MMA(0, 1, At, B1); PG8_BAR; PG8_SCHED;
	v_mfma_f32_16x16x32_bf16 v[90:93], v[144:147], v[176:179], v[90:93]
	v_mfma_f32_16x16x32_bf16 v[94:97], v[152:155], v[176:179], v[94:97]
	v_mfma_f32_16x16x32_bf16 v[74:77], v[144:147], v[184:187], v[74:77]
	v_mfma_f32_16x16x32_bf16 v[78:81], v[152:155], v[184:187], v[78:81]
	v_mfma_f32_16x16x32_bf16 v[122:125], v[144:147], v[204:207], v[122:125]
	v_mfma_f32_16x16x32_bf16 v[126:129], v[152:155], v[204:207], v[126:129]
	v_mfma_f32_16x16x32_bf16 v[106:109], v[144:147], v[222:225], v[106:109]
	v_mfma_f32_16x16x32_bf16 v[110:113], v[152:155], v[222:225], v[110:113]
	v_mfma_f32_16x16x32_bf16 v[90:93], v[148:151], v[180:183], v[90:93]
	v_mfma_f32_16x16x32_bf16 v[94:97], v[156:159], v[180:183], v[94:97]
	v_mfma_f32_16x16x32_bf16 v[74:77], v[148:151], v[188:191], v[74:77]
	v_mfma_f32_16x16x32_bf16 v[78:81], v[156:159], v[188:191], v[78:81]
	v_mfma_f32_16x16x32_bf16 v[122:125], v[148:151], v[218:221], v[122:125]
	v_mfma_f32_16x16x32_bf16 v[126:129], v[156:159], v[218:221], v[126:129]
	v_mfma_f32_16x16x32_bf16 v[106:109], v[148:151], v[226:229], v[106:109]
	v_mfma_f32_16x16x32_bf16 v[110:113], v[156:159], v[226:229], v[110:113]
	s_setprio 0
	s_setprio 1
	v_mfma_f32_16x16x32_bf16 v[82:85], v[160:163], v[176:179], v[82:85]
	v_mfma_f32_16x16x32_bf16 v[86:89], v[168:171], v[176:179], v[86:89]
	v_mfma_f32_16x16x32_bf16 v[66:69], v[160:163], v[184:187], v[66:69]
	v_mfma_f32_16x16x32_bf16 v[70:73], v[168:171], v[184:187], v[70:73]
	v_mfma_f32_16x16x32_bf16 v[114:117], v[160:163], v[204:207], v[114:117]
	v_mfma_f32_16x16x32_bf16 v[118:121], v[168:171], v[204:207], v[118:121]
	v_mfma_f32_16x16x32_bf16 v[102:105], v[160:163], v[222:225], v[102:105]
	v_mfma_f32_16x16x32_bf16 v[98:101], v[168:171], v[222:225], v[98:101]
	v_mfma_f32_16x16x32_bf16 v[82:85], v[164:167], v[180:183], v[82:85]
	v_mfma_f32_16x16x32_bf16 v[86:89], v[172:175], v[180:183], v[86:89]
	v_mfma_f32_16x16x32_bf16 v[66:69], v[164:167], v[188:191], v[66:69]
	v_mfma_f32_16x16x32_bf16 v[70:73], v[172:175], v[188:191], v[70:73]
	v_mfma_f32_16x16x32_bf16 v[114:117], v[164:167], v[218:221], v[114:117]
	v_mfma_f32_16x16x32_bf16 v[118:121], v[172:175], v[218:221], v[118:121]
	v_mfma_f32_16x16x32_bf16 v[102:105], v[164:167], v[226:229], v[102:105]
	v_mfma_f32_16x16x32_bf16 v[98:101], v[172:175], v[226:229], v[98:101]
	s_barrier
	s_setprio 0
	s_add_i32 s39, 0, 0x18000
	s_add_i32 s40, 0, 0x1c000
	v_add_u32_e32 v156, s39, v142
	v_add_u32_e32 v172, s40, v142
	ds_read_b128 v[144:147], v156
	ds_read_b128 v[148:151], v156 offset:1024
	ds_read_b128 v[152:155], v156 offset:2048
	ds_read_b128 v[156:159], v156 offset:3072
	ds_read_b128 v[160:163], v172
	ds_read_b128 v[164:167], v172 offset:1024
	ds_read_b128 v[168:171], v172 offset:2048
	ds_read_b128 v[172:175], v172 offset:3072
	s_add_u32 s18, s24, 0x160000
	s_addc_u32 s19, s25, 0
	s_mov_b32 m0, s11
	v_lshl_add_u64 v[232:233], s[18:19], 0, v[132:133]
	ds_read_b128 v[176:179], v143 offset:32768
	ds_read_b128 v[180:183], v143 offset:33792
	ds_read_b128 v[184:187], v143 offset:34816
	ds_read_b128 v[188:191], v143 offset:35840
	ds_read_b128 v[204:207], v143 offset:36864
	ds_read_b128 v[218:221], v143 offset:37888
	ds_read_b128 v[222:225], v143 offset:38912
	ds_read_b128 v[226:229], v143 offset:39936
	global_load_lds_dwordx4 v[232:233], off
	v_lshl_add_u64 v[232:233], s[18:19], 0, v[134:135]
	s_mov_b32 m0, s27
	s_nop 0
	global_load_lds_dwordx4 v[232:233], off
	s_waitcnt vmcnt(8)
	s_waitcnt lgkmcnt(0)
	s_setprio 1
	s_barrier
	v_mfma_f32_16x16x32_bf16 v[58:61], v[144:147], v[176:179], v[58:61]
	v_mfma_f32_16x16x32_bf16 v[62:65], v[152:155], v[176:179], v[62:65]
	v_mfma_f32_16x16x32_bf16 v[42:45], v[144:147], v[184:187], v[42:45]
	v_mfma_f32_16x16x32_bf16 v[46:49], v[152:155], v[184:187], v[46:49]
	v_mfma_f32_16x16x32_bf16 v[26:29], v[144:147], v[204:207], v[26:29]
	v_mfma_f32_16x16x32_bf16 v[30:33], v[152:155], v[204:207], v[30:33]
	v_mfma_f32_16x16x32_bf16 v[10:13], v[144:147], v[222:225], v[10:13]
	v_mfma_f32_16x16x32_bf16 v[14:17], v[152:155], v[222:225], v[14:17]
	v_mfma_f32_16x16x32_bf16 v[58:61], v[148:151], v[180:183], v[58:61]
	v_mfma_f32_16x16x32_bf16 v[62:65], v[156:159], v[180:183], v[62:65]
	v_mfma_f32_16x16x32_bf16 v[42:45], v[148:151], v[188:191], v[42:45]
	v_mfma_f32_16x16x32_bf16 v[46:49], v[156:159], v[188:191], v[46:49]
	v_mfma_f32_16x16x32_bf16 v[26:29], v[148:151], v[218:221], v[26:29]
	v_mfma_f32_16x16x32_bf16 v[30:33], v[156:159], v[218:221], v[30:33]
	v_mfma_f32_16x16x32_bf16 v[10:13], v[148:151], v[226:229], v[10:13]
	v_mfma_f32_16x16x32_bf16 v[14:17], v[156:159], v[226:229], v[14:17]
	s_setprio 0
	s_setprio 1
	v_mfma_f32_16x16x32_bf16 v[50:53], v[160:163], v[176:179], v[50:53]
	v_mfma_f32_16x16x32_bf16 v[54:57], v[168:171], v[176:179], v[54:57]
	v_mfma_f32_16x16x32_bf16 v[34:37], v[160:163], v[184:187], v[34:37]
	v_mfma_f32_16x16x32_bf16 v[38:41], v[168:171], v[184:187], v[38:41]
	v_mfma_f32_16x16x32_bf16 v[18:21], v[160:163], v[204:207], v[18:21]
	v_mfma_f32_16x16x32_bf16 v[22:25], v[168:171], v[204:207], v[22:25]
	v_mfma_f32_16x16x32_bf16 v[2:5], v[160:163], v[222:225], v[2:5]
	v_mfma_f32_16x16x32_bf16 v[6:9], v[168:171], v[222:225], v[6:9]
	v_mfma_f32_16x16x32_bf16 v[50:53], v[164:167], v[180:183], v[50:53]
	v_mfma_f32_16x16x32_bf16 v[54:57], v[172:175], v[180:183], v[54:57]
	v_mfma_f32_16x16x32_bf16 v[34:37], v[164:167], v[188:191], v[34:37]
	v_mfma_f32_16x16x32_bf16 v[38:41], v[172:175], v[188:191], v[38:41]
	v_mfma_f32_16x16x32_bf16 v[18:21], v[164:167], v[218:221], v[18:21]
	v_mfma_f32_16x16x32_bf16 v[22:25], v[172:175], v[218:221], v[22:25]
	v_mfma_f32_16x16x32_bf16 v[2:5], v[164:167], v[226:229], v[2:5]
	v_mfma_f32_16x16x32_bf16 v[6:9], v[172:175], v[226:229], v[6:9]
	s_barrier
; #define PG8_STAGE(bufoff, gbase, voff) do { _Pragma("unroll") for (int _i = 0; _i < 2; ++_i) \
;         __builtin_amdgcn_global_load_lds((const unsigned*)((const char*)(gbase) + (voff)[_i]), (PG8_LAS unsigned*)(lds + (bufoff) + ldsw + _i * 8192), 16, 0, 0); } while (0)
; #define PG8_LDA(dst, b, h) do { _Pragma("unroll") for (int m = 0; m < 4; ++m) _Pragma("unroll") for (int k = 0; k < 2; ++k) dst[m][k] = *(const PG8_LAS bf16x8*)(lds + PG8_SA(b, h) + aoff + m * 2048 + k * 1024); } while (0)
; #define PG8_MMA(ai, bj, At, Bt) do { __builtin_amdgcn_s_setprio(1); _Pragma("unroll") for (int m = 0; m < 4; ++m) _Pragma("unroll") for (int n = 0; n < 2; ++n) _Pragma("unroll") for (int k = 0; k < 2; ++k) \
;         acc[ai][bj][m][n] = __builtin_amdgcn_mfma_f32_16x16x32_bf16(Bt[n][k], At[m][k], acc[ai][bj][m][n], 0, 0, 0); __builtin_amdgcn_s_setprio(0); } while (0)
; #define PG8_WAIT_V(n) asm volatile("s_waitcnt vmcnt(" #n ")" ::: "memory")
; #define PG8_WAIT_L(n) asm volatile("s_waitcnt lgkmcnt(" #n ")" ::: "memory")
; #define PG8_BAR __builtin_amdgcn_s_barrier()
; #define PG8_SCHED __builtin_amdgcn_sched_barrier(0)
; template <class Epi, class Sched, bool ALIGN_EPI = false, bool SP2 = false>
; __device__ __forceinline__ void gemm_phase(PG8_LAS unsigned char* lds, const Gemm g, const Sched& S, const Epi& E) {
;     ...
;             PG8_LDA(At, 1, 1); PG8_STAGE(PG8_SB(1, 0), b3, voffB); PG8_STAGE(PG8_SB(1, 1), b3 + hstep, voffB); PG8_STAGE(PG8_SA(1, 0), a3, voffA);
;             PG8_WAIT_V(8); PG8_WAIT_L(0); PG8_BAR; PG8_MMA(1, 0, At, B0); PG8_MMA(1, 1, At, B1); PG8_BAR; PG8_SCHED;
;     ...
;         }
;         if constexpr (ALIGN_EPI) { if (wr == 0) PG8_BAR; }
	s_setprio 0
	s_add_i32 s18, s39, s2
	v_lshl_add_u64 v[192:193], v[192:193], 0, s[56:57]
	s_mov_b32 m0, s18
	ds_read_b128 v[176:179], v143 offset:49152
	ds_read_b128 v[180:183], v143 offset:50176
	ds_read_b128 v[184:187], v143 offset:51200
	ds_read_b128 v[188:191], v143 offset:52224
	ds_read_b128 v[204:207], v143 offset:53248
	ds_read_b128 v[218:221], v143 offset:54272
	ds_read_b128 v[222:225], v143 offset:55296
	ds_read_b128 v[226:229], v143 offset:56320
	global_load_lds_dwordx4 v[192:193], off
	s_add_i32 m0, s18, 0x2000
	s_add_u32 s18, s22, 0x160080
	v_lshl_add_u64 v[192:193], v[200:201], 0, s[56:57]
	s_addc_u32 s19, s23, 0
	s_add_i32 s22, s40, s2
	global_load_lds_dwordx4 v[192:193], off
	s_nop 0
	s_mov_b32 m0, s22
	s_nop 0
	global_load_lds_dwordx4 v0, s[18:19]
	s_nop 0
	s_add_i32 m0, s22, 0x2000
	s_nop 0
	global_load_lds_dwordx4 v136, s[18:19]
	v_lshl_add_u64 v[192:193], v[202:203], 0, s[56:57]
	s_mov_b32 m0, s33
	s_nop 0
	global_load_lds_dwordx4 v[192:193], off
	v_lshl_add_u64 v[192:193], v[230:231], 0, s[56:57]
	s_mov_b32 m0, s37
	s_nop 0
	global_load_lds_dwordx4 v[192:193], off
	s_waitcnt vmcnt(8)
	s_waitcnt lgkmcnt(0)
	s_setprio 1
	s_barrier
	v_mfma_f32_16x16x32_bf16 v[90:93], v[144:147], v[176:179], v[90:93]
	v_mfma_f32_16x16x32_bf16 v[94:97], v[152:155], v[176:179], v[94:97]
	v_mfma_f32_16x16x32_bf16 v[74:77], v[144:147], v[184:187], v[74:77]
	v_mfma_f32_16x16x32_bf16 v[78:81], v[152:155], v[184:187], v[78:81]
	v_mfma_f32_16x16x32_bf16 v[122:125], v[144:147], v[204:207], v[122:125]
	v_mfma_f32_16x16x32_bf16 v[126:129], v[152:155], v[204:207], v[126:129]
	v_mfma_f32_16x16x32_bf16 v[106:109], v[144:147], v[222:225], v[106:109]
	v_mfma_f32_16x16x32_bf16 v[110:113], v[152:155], v[222:225], v[110:113]
	v_mfma_f32_16x16x32_bf16 v[90:93], v[148:151], v[180:183], v[90:93]
	v_mfma_f32_16x16x32_bf16 v[94:97], v[156:159], v[180:183], v[94:97]
	v_mfma_f32_16x16x32_bf16 v[74:77], v[148:151], v[188:191], v[74:77]
	v_mfma_f32_16x16x32_bf16 v[78:81], v[156:159], v[188:191], v[78:81]
	v_mfma_f32_16x16x32_bf16 v[122:125], v[148:151], v[218:221], v[122:125]
	v_mfma_f32_16x16x32_bf16 v[126:129], v[156:159], v[218:221], v[126:129]
	v_mfma_f32_16x16x32_bf16 v[106:109], v[148:151], v[226:229], v[106:109]
	v_mfma_f32_16x16x32_bf16 v[110:113], v[156:159], v[226:229], v[110:113]
	s_setprio 0
	s_setprio 1
	v_mfma_f32_16x16x32_bf16 v[82:85], v[160:163], v[176:179], v[82:85]
	v_mfma_f32_16x16x32_bf16 v[86:89], v[168:171], v[176:179], v[86:89]
	v_mfma_f32_16x16x32_bf16 v[66:69], v[160:163], v[184:187], v[66:69]
	v_mfma_f32_16x16x32_bf16 v[70:73], v[168:171], v[184:187], v[70:73]
	v_mfma_f32_16x16x32_bf16 v[114:117], v[160:163], v[204:207], v[114:117]
	v_mfma_f32_16x16x32_bf16 v[118:121], v[168:171], v[204:207], v[118:121]
	v_mfma_f32_16x16x32_bf16 v[102:105], v[160:163], v[222:225], v[102:105]
	v_mfma_f32_16x16x32_bf16 v[98:101], v[168:171], v[222:225], v[98:101]
	v_mfma_f32_16x16x32_bf16 v[82:85], v[164:167], v[180:183], v[82:85]
	v_mfma_f32_16x16x32_bf16 v[86:89], v[172:175], v[180:183], v[86:89]
	v_mfma_f32_16x16x32_bf16 v[66:69], v[164:167], v[188:191], v[66:69]
	v_mfma_f32_16x16x32_bf16 v[70:73], v[172:175], v[188:191], v[70:73]
	v_mfma_f32_16x16x32_bf16 v[114:117], v[164:167], v[218:221], v[114:117]
	v_mfma_f32_16x16x32_bf16 v[118:121], v[172:175], v[218:221], v[118:121]
	v_mfma_f32_16x16x32_bf16 v[102:105], v[164:167], v[226:229], v[102:105]
	v_mfma_f32_16x16x32_bf16 v[98:101], v[172:175], v[226:229], v[98:101]
	s_barrier
	s_setprio 0
	s_add_i32 s38, s38, 2
	s_cmp_gt_u32 s38, 19
	s_mov_b64 s[18:19], s[20:21]
	s_cbranch_scc0 .LBB0_1027
	s_cmpk_lt_u32 s1, 0x100
	s_cbranch_scc0 .LBB0_1030
	s_barrier
